# non-temporal hint on the once-read residual (xold) loads of the P3/P7/P9 epilogues
# baseline (speedup 1.0000x reference)
; #define PG8_LAS __attribute__((address_space(3)))
; __device__ __forceinline__ u32x4 pack8(const f32x4 a, const f32x4 b) { u32x4 w; w.x = cvt_pk_bf16(a[0], a[1]); w.y = cvt_pk_bf16(a[2], a[3]); w.z = cvt_pk_bf16(b[0], b[1]); w.w = cvt_pk_bf16(b[2], b[3]); return w; }
;     __device__ __forceinline__ void operator()(const f32x4 (&acc)[2][2][4][2], const Unit& u, int wr, int wc, int fr, int fq) const {
;     ...
;         const int b = u.pm >> 5, col0 = u.pn * BM + wc * 64 + fq * 8;
;         PG8_LAS unsigned char* st = stg + (wr * 4 + wc) * 1024;
;         f32x4 gv[2][2], cs[2][2];
; #pragma unroll
;         for (int bj = 0; bj < 2; ++bj)
; #pragma unroll
;             for (int n = 0; n < 2; ++n) { const int c = col0 + bj * 32 + 4 * n; gv[bj][n] = *(const f32x4*)(gate + (size_t)b * NMODC + c) * (HALFG ? 0.5f : 1.0f);
;                 cs[bj][n] = (f32x4){0.f, 0.f, 0.f, 0.f}; if (XS) cs[bj][n] = *(const f32x4*)(gcol + c) * (*(const f32x4*)(scm + (size_t)b * NMODC + c) + 1.0f); }
;         u32x4 c16[2], n16[2]; f32x4 c32[2][2], n32[2][2];
;     ...
;         RES_LOAD(c16, c32, 0);
; #pragma unroll
;         for (int r = 0; r < 8; ++r) { const int ai = r >> 2, m = r & 3; const int row = EPI_ROW; float sq = 0.f;
;             if (r < 7) RES_LOAD(n16, n32, r + 1);
;             u32x4 pn_[2], ps_[2];
; #pragma unroll
;             for (int bj = 0; bj < 2; ++bj) {
;                 f32x4 o0, o1;
;                 if (XOLD16) unpack8(c16[bj], o0, o1); else { o0 = c32[bj][0]; o1 = c32[bj][1]; }
;                 const f32x4 v0 = o0 + gv[bj][0] * acc[ai][bj][m][0], v1 = o1 + gv[bj][1] * acc[ai][bj][m][1];
;                 pn_[bj] = pack8(v0, v1);
;                 sq += ((v0[0] * v0[0] + v0[1] * v0[1]) + (v0[2] * v0[2] + v0[3] * v0[3])) + ((v1[0] * v1[0] + v1[1] * v1[1]) + (v1[2] * v1[2] + v1[3] * v1[3]));
;                 if (XS) ps_[bj] = pack8(v0 * cs[bj][0], v1 * cs[bj][1]); }
;             { const size_t seg = (size_t)(row - fr) * DM + u.pn * BM + wc * 64;
;               store_lines(st, pn_[0], pn_[1], fr, fq, xnew + seg, DM);
;               if (XS) store_lines(st, ps_[0], ps_[1], fr, fq, xs + seg, DM); }
.LBB0_292:
	s_lshl_b32 s0, s16, 8
	v_mov_b32_e32 v227, v1
	v_mov_b32_e32 v230, v221
	s_ashr_i32 s1, s38, 5
	s_or_b32 s4, s0, s28
	s_mul_hi_i32 s6, s1, 0x9000
	v_lshl_add_u32 v200, v230, 3, s4
	s_mul_i32 s1, s1, 0x9000
	s_add_u32 s4, s55, s1
	v_ashrrev_i32_e32 v201, 31, v200
	s_addc_u32 s5, s56, s6
	v_lshlrev_b64 v[130:131], 2, v[200:201]
	v_lshl_add_u64 v[132:133], s[4:5], 0, v[130:131]
	s_add_u32 s4, s59, s1
	s_addc_u32 s5, s60, s6
	s_lshl_b32 s1, s38, 8
	s_add_i32 s40, s1, s62
	v_add_u32_e32 v202, s40, v227
	global_load_dwordx4 v[164:167], v[132:133], off nt
	global_load_dwordx4 v[168:171], v[132:133], off offset:16 nt
	global_load_dwordx4 v[172:175], v[132:133], off offset:144 nt
	global_load_dwordx4 v[178:181], v[132:133], off offset:128 nt
	v_lshl_add_u64 v[132:133], s[4:5], 0, v[130:131]
	v_ashrrev_i32_e32 v203, 31, v202
	global_load_dwordx4 v[182:185], v[132:133], off nt
	global_load_dwordx4 v[186:189], v[132:133], off offset:16 nt
	v_lshl_add_u64 v[134:135], s[14:15], 0, v[130:131]
	global_load_dwordx4 v[204:207], v[132:133], off offset:144 nt
	global_load_dwordx4 v[208:211], v[132:133], off offset:128 nt
	global_load_dwordx4 v[212:215], v[134:135], off offset:16 nt
	global_load_dwordx4 v[216:219], v[134:135], off nt
	global_load_dwordx4 v[232:235], v[134:135], off offset:144 nt
	global_load_dwordx4 v[236:239], v[134:135], off offset:128 nt
	v_lshlrev_b64 v[132:133], 12, v[202:203]
	v_lshl_add_u64 v[132:133], s[10:11], 0, v[132:133]
	v_lshl_add_u64 v[132:133], v[132:133], 0, v[130:131]
	global_load_dwordx4 v[240:243], v[132:133], off nt
	global_load_dwordx4 v[244:247], v[132:133], off offset:16 nt
	global_load_dwordx4 v[248:251], v[132:133], off offset:128 nt
	global_load_dwordx4 v[160:163], v[132:133], off offset:144 nt
	v_add_u32_e32 v132, 16, v202
	v_ashrrev_i32_e32 v133, 31, v132
	v_lshlrev_b64 v[132:133], 12, v[132:133]
	v_lshl_add_u64 v[132:133], s[10:11], 0, v[132:133]
	v_lshl_add_u64 v[134:135], v[132:133], 0, v[130:131]
	global_load_dwordx4 v[138:141], v[134:135], off offset:16 nt
	global_load_dwordx4 v[142:145], v[134:135], off nt
	global_load_dwordx4 v[130:133], v[134:135], off offset:144 nt
	s_nop 0
	global_load_dwordx4 v[134:137], v[134:135], off offset:128 nt
	v_lshlrev_b32_e32 v176, 7, v227
	v_and_b32_e32 v176, 0x380, v176
	v_add_u32_e32 v228, s67, v176
	v_lshlrev_b32_e32 v154, 4, v230
	v_cmp_gt_u32_e32 vcc, 8, v227
	v_add_u32_e32 v229, v228, v154
	s_waitcnt vmcnt(0)
	v_pk_mul_f32 v[194:195], v[166:167], 0.5 op_sel_hi:[1,0]
	v_pk_mul_f32 v[196:197], v[164:165], 0.5 op_sel_hi:[1,0]
	v_pk_mul_f32 v[192:193], v[170:171], 0.5 op_sel_hi:[1,0]
	v_pk_mul_f32 v[190:191], v[168:169], 0.5 op_sel_hi:[1,0]
	v_pk_mul_f32 v[176:177], v[180:181], 0.5 op_sel_hi:[1,0]
	v_pk_mul_f32 v[178:179], v[178:179], 0.5 op_sel_hi:[1,0]
	v_pk_add_f32 v[164:165], v[184:185], 1.0 op_sel_hi:[1,0]
	v_pk_add_f32 v[166:167], v[182:183], 1.0 op_sel_hi:[1,0]
	v_pk_add_f32 v[168:169], v[188:189], 1.0 op_sel_hi:[1,0]
	v_pk_add_f32 v[170:171], v[186:187], 1.0 op_sel_hi:[1,0]
	v_pk_add_f32 v[180:181], v[210:211], 1.0 op_sel_hi:[1,0]
	v_pk_add_f32 v[198:199], v[208:209], 1.0 op_sel_hi:[1,0]
	v_pk_add_f32 v[206:207], v[206:207], 1.0 op_sel_hi:[1,0]
	v_pk_mul_f32 v[174:175], v[174:175], 0.5 op_sel_hi:[1,0]
	v_pk_mul_f32 v[172:173], v[172:173], 0.5 op_sel_hi:[1,0]
	v_pk_add_f32 v[204:205], v[204:205], 1.0 op_sel_hi:[1,0]
	v_pk_mul_f32 v[186:187], v[218:219], v[164:165]
	v_pk_mul_f32 v[188:189], v[216:217], v[166:167]
	v_pk_mul_f32 v[182:183], v[214:215], v[168:169]
	v_pk_mul_f32 v[184:185], v[212:213], v[170:171]
	v_pk_mul_f32 v[168:169], v[238:239], v[180:181]
	v_pk_mul_f32 v[170:171], v[236:237], v[198:199]
	v_pk_mul_f32 v[164:165], v[234:235], v[206:207]
	v_pk_fma_f32 v[206:207], v[128:129], v[194:195], v[242:243]
	v_pk_fma_f32 v[210:211], v[126:127], v[196:197], v[240:241]
	v_pk_fma_f32 v[214:215], v[120:121], v[176:177], v[250:251]
	v_pk_fma_f32 v[218:219], v[118:119], v[178:179], v[248:249]
	v_pk_mul_f32 v[166:167], v[232:233], v[204:205]
	v_pk_fma_f32 v[204:205], v[124:125], v[192:193], v[246:247]
	v_pk_fma_f32 v[208:209], v[122:123], v[190:191], v[244:245]
	v_pk_mul_f32 v[124:125], v[186:187], v[206:207]
	v_pk_mul_f32 v[122:123], v[188:189], v[210:211]
	v_pk_fma_f32 v[212:213], v[116:117], v[174:175], v[162:163]
	v_pk_fma_f32 v[216:217], v[114:115], v[172:173], v[160:161]
	v_pk_mul_f32 v[116:117], v[168:169], v[214:215]
	v_pk_mul_f32 v[114:115], v[170:171], v[218:219]
	v_cvt_pk_bf16_f32 v126, v210, v211
	v_cvt_pk_bf16_f32 v127, v206, v207
	v_cvt_pk_bf16_f32 v128, v208, v209
	v_cvt_pk_bf16_f32 v129, v204, v205
	v_pk_mul_f32 v[180:181], v[182:183], v[204:205]
	v_pk_mul_f32 v[198:199], v[184:185], v[208:209]
	v_cvt_pk_bf16_f32 v122, v122, v123
	v_cvt_pk_bf16_f32 v123, v124, v125
	v_pk_mul_f32 v[160:161], v[164:165], v[212:213]
	v_cvt_pk_bf16_f32 v124, v198, v199
	v_cvt_pk_bf16_f32 v125, v180, v181
	v_cvt_pk_bf16_f32 v118, v218, v219
	v_cvt_pk_bf16_f32 v119, v214, v215
	v_cvt_pk_bf16_f32 v120, v216, v217
	v_cvt_pk_bf16_f32 v121, v212, v213
	v_pk_mul_f32 v[162:163], v[166:167], v[216:217]
	v_cvt_pk_bf16_f32 v114, v114, v115
	v_cvt_pk_bf16_f32 v115, v116, v117
	s_nop 0
	v_cvt_pk_bf16_f32 v116, v162, v163
	v_cvt_pk_bf16_f32 v117, v160, v161
	s_and_saveexec_b64 s[4:5], vcc
	s_cbranch_execz .LBB0_294
	ds_write_b128 v229, v[126:129]
	ds_write_b128 v229, v[118:121] offset:64

; __device__ __forceinline__ u32x4 pack8(const f32x4 a, const f32x4 b) { u32x4 w; w.x = cvt_pk_bf16(a[0], a[1]); w.y = cvt_pk_bf16(a[2], a[3]); w.z = cvt_pk_bf16(b[0], b[1]); w.w = cvt_pk_bf16(b[2], b[3]); return w; }
;     __device__ __forceinline__ void operator()(const f32x4 (&acc)[2][2][4][2], const Unit& u, int wr, int wc, int fr, int fq) const {
;     ...
;         RES_LOAD(c16, c32, 0);
; #pragma unroll
;         for (int r = 0; r < 8; ++r) { const int ai = r >> 2, m = r & 3; const int row = EPI_ROW; float sq = 0.f;
;             if (r < 7) RES_LOAD(n16, n32, r + 1);
;             u32x4 pn_[2], ps_[2];
; #pragma unroll
;             for (int bj = 0; bj < 2; ++bj) {
;                 f32x4 o0, o1;
;                 if (XOLD16) unpack8(c16[bj], o0, o1); else { o0 = c32[bj][0]; o1 = c32[bj][1]; }
;                 const f32x4 v0 = o0 + gv[bj][0] * acc[ai][bj][m][0], v1 = o1 + gv[bj][1] * acc[ai][bj][m][1];
;                 pn_[bj] = pack8(v0, v1);
;                 sq += ((v0[0] * v0[0] + v0[1] * v0[1]) + (v0[2] * v0[2] + v0[3] * v0[3])) + ((v1[0] * v1[0] + v1[1] * v1[1]) + (v1[2] * v1[2] + v1[3] * v1[3]));
;                 if (XS) ps_[bj] = pack8(v0 * cs[bj][0], v1 * cs[bj][1]); }
;             { const size_t seg = (size_t)(row - fr) * DM + u.pn * BM + wc * 64;
;               store_lines(st, pn_[0], pn_[1], fr, fq, xnew + seg, DM);
;               if (XS) store_lines(st, ps_[0], ps_[1], fr, fq, xs + seg, DM); }
.LBB0_302:
	s_or_b64 exec, exec, s[0:1]
	v_add_u32_e32 v114, 32, v202
	s_waitcnt lgkmcnt(0)
	v_ashrrev_i32_e32 v115, 31, v114
	v_lshlrev_b64 v[114:115], 12, v[114:115]
	v_lshl_add_u64 v[114:115], s[10:11], 0, v[114:115]
	v_lshl_add_u64 v[118:119], v[200:201], 2, v[114:115]
	global_load_dwordx4 v[122:125], v[118:119], off offset:16 nt
	global_load_dwordx4 v[126:129], v[118:119], off nt
	global_load_dwordx4 v[114:117], v[118:119], off offset:144 nt
	s_nop 0
	global_load_dwordx4 v[118:121], v[118:119], off offset:128 nt
	v_pk_fma_f32 v[144:145], v[112:113], v[194:195], v[144:145]
	v_pk_fma_f32 v[142:143], v[110:111], v[196:197], v[142:143]
	v_pk_fma_f32 v[140:141], v[108:109], v[192:193], v[140:141]
	v_pk_fma_f32 v[138:139], v[106:107], v[190:191], v[138:139]
	v_pk_fma_f32 v[136:137], v[104:105], v[176:177], v[136:137]
	v_pk_fma_f32 v[134:135], v[102:103], v[178:179], v[134:135]
	v_pk_mul_f32 v[108:109], v[186:187], v[144:145]
	v_pk_mul_f32 v[106:107], v[188:189], v[142:143]
	v_pk_mul_f32 v[160:161], v[182:183], v[140:141]
	v_pk_mul_f32 v[162:163], v[184:185], v[138:139]
	v_pk_fma_f32 v[132:133], v[100:101], v[174:175], v[132:133]
	v_pk_fma_f32 v[130:131], v[98:99], v[172:173], v[130:131]
	v_pk_mul_f32 v[100:101], v[168:169], v[136:137]
	v_pk_mul_f32 v[98:99], v[170:171], v[134:135]
	v_cvt_pk_bf16_f32 v110, v142, v143
	v_cvt_pk_bf16_f32 v111, v144, v145
	v_cvt_pk_bf16_f32 v112, v138, v139
	v_cvt_pk_bf16_f32 v113, v140, v141
	v_cvt_pk_bf16_f32 v106, v106, v107
	v_cvt_pk_bf16_f32 v107, v108, v109
	v_cvt_pk_bf16_f32 v108, v162, v163
	v_cvt_pk_bf16_f32 v109, v160, v161
	v_cvt_pk_bf16_f32 v102, v134, v135
	v_cvt_pk_bf16_f32 v103, v136, v137
	v_cvt_pk_bf16_f32 v104, v130, v131
	v_cvt_pk_bf16_f32 v105, v132, v133
	v_pk_mul_f32 v[160:161], v[164:165], v[132:133]
	v_pk_mul_f32 v[162:163], v[166:167], v[130:131]
	v_cvt_pk_bf16_f32 v98, v98, v99
	v_cvt_pk_bf16_f32 v99, v100, v101
	s_nop 0
	v_cvt_pk_bf16_f32 v100, v162, v163
	v_cvt_pk_bf16_f32 v101, v160, v161
	s_and_saveexec_b64 s[0:1], vcc
	s_cbranch_execz .LBB0_304
	ds_write_b128 v229, v[110:113]
	ds_write_b128 v229, v[102:105] offset:64

; __device__ __forceinline__ u32x4 pack8(const f32x4 a, const f32x4 b) { u32x4 w; w.x = cvt_pk_bf16(a[0], a[1]); w.y = cvt_pk_bf16(a[2], a[3]); w.z = cvt_pk_bf16(b[0], b[1]); w.w = cvt_pk_bf16(b[2], b[3]); return w; }
;     __device__ __forceinline__ void operator()(const f32x4 (&acc)[2][2][4][2], const Unit& u, int wr, int wc, int fr, int fq) const {
;     ...
;         RES_LOAD(c16, c32, 0);
; #pragma unroll
;         for (int r = 0; r < 8; ++r) { const int ai = r >> 2, m = r & 3; const int row = EPI_ROW; float sq = 0.f;
;             if (r < 7) RES_LOAD(n16, n32, r + 1);
;             u32x4 pn_[2], ps_[2];
; #pragma unroll
;             for (int bj = 0; bj < 2; ++bj) {
;                 f32x4 o0, o1;
;                 if (XOLD16) unpack8(c16[bj], o0, o1); else { o0 = c32[bj][0]; o1 = c32[bj][1]; }
;                 const f32x4 v0 = o0 + gv[bj][0] * acc[ai][bj][m][0], v1 = o1 + gv[bj][1] * acc[ai][bj][m][1];
;                 pn_[bj] = pack8(v0, v1);
;                 sq += ((v0[0] * v0[0] + v0[1] * v0[1]) + (v0[2] * v0[2] + v0[3] * v0[3])) + ((v1[0] * v1[0] + v1[1] * v1[1]) + (v1[2] * v1[2] + v1[3] * v1[3]));
;                 if (XS) ps_[bj] = pack8(v0 * cs[bj][0], v1 * cs[bj][1]); }
;             { const size_t seg = (size_t)(row - fr) * DM + u.pn * BM + wc * 64;
;               store_lines(st, pn_[0], pn_[1], fr, fq, xnew + seg, DM);
;               if (XS) store_lines(st, ps_[0], ps_[1], fr, fq, xs + seg, DM); }
.LBB0_312:
	s_or_b64 exec, exec, s[42:43]
	v_add_u32_e32 v98, 48, v202
	s_waitcnt lgkmcnt(0)
	v_ashrrev_i32_e32 v99, 31, v98
	v_lshlrev_b64 v[98:99], 12, v[98:99]
	v_lshl_add_u64 v[98:99], s[10:11], 0, v[98:99]
	v_lshl_add_u64 v[102:103], v[200:201], 2, v[98:99]
	global_load_dwordx4 v[106:109], v[102:103], off offset:16 nt
	global_load_dwordx4 v[110:113], v[102:103], off nt
	global_load_dwordx4 v[98:101], v[102:103], off offset:144 nt
	s_nop 0
	global_load_dwordx4 v[102:105], v[102:103], off offset:128 nt
	s_waitcnt vmcnt(10)
	v_pk_fma_f32 v[128:129], v[96:97], v[194:195], v[128:129]
	v_pk_fma_f32 v[126:127], v[94:95], v[196:197], v[126:127]
	v_pk_fma_f32 v[124:125], v[92:93], v[192:193], v[124:125]
	v_pk_fma_f32 v[122:123], v[90:91], v[190:191], v[122:123]
	s_waitcnt vmcnt(8)
	v_pk_fma_f32 v[120:121], v[88:89], v[176:177], v[120:121]
	v_pk_fma_f32 v[118:119], v[86:87], v[178:179], v[118:119]
	v_pk_mul_f32 v[92:93], v[186:187], v[128:129]
	v_pk_mul_f32 v[90:91], v[188:189], v[126:127]
	v_pk_mul_f32 v[130:131], v[182:183], v[124:125]
	v_pk_mul_f32 v[132:133], v[184:185], v[122:123]
	v_pk_fma_f32 v[116:117], v[84:85], v[174:175], v[116:117]
	v_pk_fma_f32 v[114:115], v[82:83], v[172:173], v[114:115]
	v_pk_mul_f32 v[84:85], v[168:169], v[120:121]
	v_pk_mul_f32 v[82:83], v[170:171], v[118:119]
	v_cvt_pk_bf16_f32 v94, v126, v127
	v_cvt_pk_bf16_f32 v95, v128, v129
	v_cvt_pk_bf16_f32 v96, v122, v123
	v_cvt_pk_bf16_f32 v97, v124, v125
	v_cvt_pk_bf16_f32 v90, v90, v91
	v_cvt_pk_bf16_f32 v91, v92, v93
	v_cvt_pk_bf16_f32 v92, v132, v133
	v_cvt_pk_bf16_f32 v93, v130, v131
	v_cvt_pk_bf16_f32 v86, v118, v119
	v_cvt_pk_bf16_f32 v87, v120, v121
	v_cvt_pk_bf16_f32 v88, v114, v115
	v_cvt_pk_bf16_f32 v89, v116, v117
	v_pk_mul_f32 v[130:131], v[164:165], v[116:117]
	v_pk_mul_f32 v[132:133], v[166:167], v[114:115]
	v_cvt_pk_bf16_f32 v82, v82, v83
	v_cvt_pk_bf16_f32 v83, v84, v85
	s_nop 0
	v_cvt_pk_bf16_f32 v84, v132, v133
	v_cvt_pk_bf16_f32 v85, v130, v131
	s_and_saveexec_b64 s[0:1], vcc
	s_cbranch_execz .LBB0_314
	ds_write_b128 v229, v[94:97]
	ds_write_b128 v229, v[86:89] offset:64

; __device__ __forceinline__ u32x4 pack8(const f32x4 a, const f32x4 b) { u32x4 w; w.x = cvt_pk_bf16(a[0], a[1]); w.y = cvt_pk_bf16(a[2], a[3]); w.z = cvt_pk_bf16(b[0], b[1]); w.w = cvt_pk_bf16(b[2], b[3]); return w; }
;     __device__ __forceinline__ void operator()(const f32x4 (&acc)[2][2][4][2], const Unit& u, int wr, int wc, int fr, int fq) const {
;     ...
;         RES_LOAD(c16, c32, 0);
; #pragma unroll
;         for (int r = 0; r < 8; ++r) { const int ai = r >> 2, m = r & 3; const int row = EPI_ROW; float sq = 0.f;
;             if (r < 7) RES_LOAD(n16, n32, r + 1);
;             u32x4 pn_[2], ps_[2];
; #pragma unroll
;             for (int bj = 0; bj < 2; ++bj) {
;                 f32x4 o0, o1;
;                 if (XOLD16) unpack8(c16[bj], o0, o1); else { o0 = c32[bj][0]; o1 = c32[bj][1]; }
;                 const f32x4 v0 = o0 + gv[bj][0] * acc[ai][bj][m][0], v1 = o1 + gv[bj][1] * acc[ai][bj][m][1];
;                 pn_[bj] = pack8(v0, v1);
;                 sq += ((v0[0] * v0[0] + v0[1] * v0[1]) + (v0[2] * v0[2] + v0[3] * v0[3])) + ((v1[0] * v1[0] + v1[1] * v1[1]) + (v1[2] * v1[2] + v1[3] * v1[3]));
;                 if (XS) ps_[bj] = pack8(v0 * cs[bj][0], v1 * cs[bj][1]); }
;             { const size_t seg = (size_t)(row - fr) * DM + u.pn * BM + wc * 64;
;               store_lines(st, pn_[0], pn_[1], fr, fq, xnew + seg, DM);
;               if (XS) store_lines(st, ps_[0], ps_[1], fr, fq, xs + seg, DM); }
.LBB0_322:
	s_or_b64 exec, exec, s[42:43]
	v_add_u32_e32 v82, 0x80, v202
	s_waitcnt lgkmcnt(0)
	v_ashrrev_i32_e32 v83, 31, v82
	v_lshlrev_b64 v[82:83], 12, v[82:83]
	v_lshl_add_u64 v[82:83], s[10:11], 0, v[82:83]
	v_lshl_add_u64 v[86:87], v[200:201], 2, v[82:83]
	global_load_dwordx4 v[90:93], v[86:87], off offset:16 nt
	global_load_dwordx4 v[94:97], v[86:87], off nt
	global_load_dwordx4 v[82:85], v[86:87], off offset:144 nt
	s_nop 0
	global_load_dwordx4 v[86:89], v[86:87], off offset:128 nt
	s_waitcnt vmcnt(10)
	v_pk_fma_f32 v[112:113], v[80:81], v[194:195], v[112:113]
	v_pk_fma_f32 v[110:111], v[78:79], v[196:197], v[110:111]
	v_pk_fma_f32 v[108:109], v[76:77], v[192:193], v[108:109]
	v_pk_fma_f32 v[106:107], v[74:75], v[190:191], v[106:107]
	s_waitcnt vmcnt(8)
	v_pk_fma_f32 v[104:105], v[72:73], v[176:177], v[104:105]
	v_pk_fma_f32 v[102:103], v[70:71], v[178:179], v[102:103]
	v_pk_mul_f32 v[76:77], v[186:187], v[112:113]
	v_pk_mul_f32 v[74:75], v[188:189], v[110:111]
	v_pk_mul_f32 v[114:115], v[182:183], v[108:109]
	v_pk_mul_f32 v[116:117], v[184:185], v[106:107]
	v_pk_fma_f32 v[100:101], v[68:69], v[174:175], v[100:101]
	v_pk_fma_f32 v[98:99], v[66:67], v[172:173], v[98:99]
	v_pk_mul_f32 v[68:69], v[168:169], v[104:105]
	v_pk_mul_f32 v[66:67], v[170:171], v[102:103]
	v_cvt_pk_bf16_f32 v78, v110, v111
	v_cvt_pk_bf16_f32 v79, v112, v113
	v_cvt_pk_bf16_f32 v80, v106, v107
	v_cvt_pk_bf16_f32 v81, v108, v109
	v_cvt_pk_bf16_f32 v74, v74, v75
	v_cvt_pk_bf16_f32 v75, v76, v77
	v_cvt_pk_bf16_f32 v76, v116, v117
	v_cvt_pk_bf16_f32 v77, v114, v115
	v_cvt_pk_bf16_f32 v70, v102, v103
	v_cvt_pk_bf16_f32 v71, v104, v105
	v_cvt_pk_bf16_f32 v72, v98, v99
	v_cvt_pk_bf16_f32 v73, v100, v101
	v_pk_mul_f32 v[114:115], v[164:165], v[100:101]
	v_pk_mul_f32 v[116:117], v[166:167], v[98:99]
	v_cvt_pk_bf16_f32 v66, v66, v67
	v_cvt_pk_bf16_f32 v67, v68, v69
	s_nop 0
	v_cvt_pk_bf16_f32 v68, v116, v117
	v_cvt_pk_bf16_f32 v69, v114, v115
	s_and_saveexec_b64 s[0:1], vcc
	s_cbranch_execz .LBB0_324
	ds_write_b128 v229, v[78:81]
	ds_write_b128 v229, v[70:73] offset:64

; __device__ __forceinline__ u32x4 pack8(const f32x4 a, const f32x4 b) { u32x4 w; w.x = cvt_pk_bf16(a[0], a[1]); w.y = cvt_pk_bf16(a[2], a[3]); w.z = cvt_pk_bf16(b[0], b[1]); w.w = cvt_pk_bf16(b[2], b[3]); return w; }
;     __device__ __forceinline__ void operator()(const f32x4 (&acc)[2][2][4][2], const Unit& u, int wr, int wc, int fr, int fq) const {
;     ...
;         RES_LOAD(c16, c32, 0);
; #pragma unroll
;         for (int r = 0; r < 8; ++r) { const int ai = r >> 2, m = r & 3; const int row = EPI_ROW; float sq = 0.f;
;             if (r < 7) RES_LOAD(n16, n32, r + 1);
;             u32x4 pn_[2], ps_[2];
; #pragma unroll
;             for (int bj = 0; bj < 2; ++bj) {
;                 f32x4 o0, o1;
;                 if (XOLD16) unpack8(c16[bj], o0, o1); else { o0 = c32[bj][0]; o1 = c32[bj][1]; }
;                 const f32x4 v0 = o0 + gv[bj][0] * acc[ai][bj][m][0], v1 = o1 + gv[bj][1] * acc[ai][bj][m][1];
;                 pn_[bj] = pack8(v0, v1);
;                 sq += ((v0[0] * v0[0] + v0[1] * v0[1]) + (v0[2] * v0[2] + v0[3] * v0[3])) + ((v1[0] * v1[0] + v1[1] * v1[1]) + (v1[2] * v1[2] + v1[3] * v1[3]));
;                 if (XS) ps_[bj] = pack8(v0 * cs[bj][0], v1 * cs[bj][1]); }
;             { const size_t seg = (size_t)(row - fr) * DM + u.pn * BM + wc * 64;
;               store_lines(st, pn_[0], pn_[1], fr, fq, xnew + seg, DM);
;               if (XS) store_lines(st, ps_[0], ps_[1], fr, fq, xs + seg, DM); }
.LBB0_332:
	s_or_b64 exec, exec, s[42:43]
	v_add_u32_e32 v66, 0x90, v202
	s_waitcnt lgkmcnt(0)
	v_ashrrev_i32_e32 v67, 31, v66
	v_lshlrev_b64 v[66:67], 12, v[66:67]
	v_lshl_add_u64 v[66:67], s[10:11], 0, v[66:67]
	v_lshl_add_u64 v[70:71], v[200:201], 2, v[66:67]
	global_load_dwordx4 v[74:77], v[70:71], off offset:16 nt
	global_load_dwordx4 v[78:81], v[70:71], off nt
	global_load_dwordx4 v[66:69], v[70:71], off offset:144 nt
	s_nop 0
	global_load_dwordx4 v[70:73], v[70:71], off offset:128 nt
	s_waitcnt vmcnt(10)
	v_pk_fma_f32 v[96:97], v[64:65], v[194:195], v[96:97]
	v_pk_fma_f32 v[94:95], v[62:63], v[196:197], v[94:95]
	v_pk_fma_f32 v[92:93], v[60:61], v[192:193], v[92:93]
	v_pk_fma_f32 v[90:91], v[58:59], v[190:191], v[90:91]
	s_waitcnt vmcnt(8)
	v_pk_fma_f32 v[88:89], v[56:57], v[176:177], v[88:89]
	v_pk_fma_f32 v[86:87], v[54:55], v[178:179], v[86:87]
	v_pk_mul_f32 v[60:61], v[186:187], v[96:97]
	v_pk_mul_f32 v[58:59], v[188:189], v[94:95]
	v_pk_mul_f32 v[98:99], v[182:183], v[92:93]
	v_pk_mul_f32 v[100:101], v[184:185], v[90:91]
	v_pk_fma_f32 v[84:85], v[52:53], v[174:175], v[84:85]
	v_pk_fma_f32 v[82:83], v[50:51], v[172:173], v[82:83]
	v_pk_mul_f32 v[52:53], v[168:169], v[88:89]
	v_pk_mul_f32 v[50:51], v[170:171], v[86:87]
	v_cvt_pk_bf16_f32 v62, v94, v95
	v_cvt_pk_bf16_f32 v63, v96, v97
	v_cvt_pk_bf16_f32 v64, v90, v91
	v_cvt_pk_bf16_f32 v65, v92, v93
	v_cvt_pk_bf16_f32 v58, v58, v59
	v_cvt_pk_bf16_f32 v59, v60, v61
	v_cvt_pk_bf16_f32 v60, v100, v101
	v_cvt_pk_bf16_f32 v61, v98, v99
	v_cvt_pk_bf16_f32 v54, v86, v87
	v_cvt_pk_bf16_f32 v55, v88, v89
	v_cvt_pk_bf16_f32 v56, v82, v83
	v_cvt_pk_bf16_f32 v57, v84, v85
	v_pk_mul_f32 v[98:99], v[164:165], v[84:85]
	v_pk_mul_f32 v[100:101], v[166:167], v[82:83]
	v_cvt_pk_bf16_f32 v50, v50, v51
	v_cvt_pk_bf16_f32 v51, v52, v53
	s_nop 0
	v_cvt_pk_bf16_f32 v52, v100, v101
	v_cvt_pk_bf16_f32 v53, v98, v99
	s_and_saveexec_b64 s[0:1], vcc
	s_cbranch_execz .LBB0_334
	ds_write_b128 v229, v[62:65]
	ds_write_b128 v229, v[54:57] offset:64

; __device__ __forceinline__ u32x4 pack8(const f32x4 a, const f32x4 b) { u32x4 w; w.x = cvt_pk_bf16(a[0], a[1]); w.y = cvt_pk_bf16(a[2], a[3]); w.z = cvt_pk_bf16(b[0], b[1]); w.w = cvt_pk_bf16(b[2], b[3]); return w; }
;     __device__ __forceinline__ void operator()(const f32x4 (&acc)[2][2][4][2], const Unit& u, int wr, int wc, int fr, int fq) const {
;     ...
;         RES_LOAD(c16, c32, 0);
; #pragma unroll
;         for (int r = 0; r < 8; ++r) { const int ai = r >> 2, m = r & 3; const int row = EPI_ROW; float sq = 0.f;
;             if (r < 7) RES_LOAD(n16, n32, r + 1);
;             u32x4 pn_[2], ps_[2];
; #pragma unroll
;             for (int bj = 0; bj < 2; ++bj) {
;                 f32x4 o0, o1;
;                 if (XOLD16) unpack8(c16[bj], o0, o1); else { o0 = c32[bj][0]; o1 = c32[bj][1]; }
;                 const f32x4 v0 = o0 + gv[bj][0] * acc[ai][bj][m][0], v1 = o1 + gv[bj][1] * acc[ai][bj][m][1];
;                 pn_[bj] = pack8(v0, v1);
;                 sq += ((v0[0] * v0[0] + v0[1] * v0[1]) + (v0[2] * v0[2] + v0[3] * v0[3])) + ((v1[0] * v1[0] + v1[1] * v1[1]) + (v1[2] * v1[2] + v1[3] * v1[3]));
;                 if (XS) ps_[bj] = pack8(v0 * cs[bj][0], v1 * cs[bj][1]); }
;             { const size_t seg = (size_t)(row - fr) * DM + u.pn * BM + wc * 64;
;               store_lines(st, pn_[0], pn_[1], fr, fq, xnew + seg, DM);
;               if (XS) store_lines(st, ps_[0], ps_[1], fr, fq, xs + seg, DM); }
.LBB0_342:
	s_or_b64 exec, exec, s[40:41]
	v_add_u32_e32 v50, 0xa0, v202
	s_waitcnt lgkmcnt(0)
	v_ashrrev_i32_e32 v51, 31, v50
	v_lshlrev_b64 v[50:51], 12, v[50:51]
	v_lshl_add_u64 v[50:51], s[10:11], 0, v[50:51]
	v_lshl_add_u64 v[54:55], v[200:201], 2, v[50:51]
	global_load_dwordx4 v[58:61], v[54:55], off offset:16 nt
	global_load_dwordx4 v[62:65], v[54:55], off nt
	global_load_dwordx4 v[50:53], v[54:55], off offset:144 nt
	s_nop 0
	global_load_dwordx4 v[54:57], v[54:55], off offset:128 nt
	s_waitcnt vmcnt(10)
	v_pk_fma_f32 v[80:81], v[48:49], v[194:195], v[80:81]
	v_pk_fma_f32 v[78:79], v[46:47], v[196:197], v[78:79]
	v_pk_fma_f32 v[76:77], v[44:45], v[192:193], v[76:77]
	v_pk_fma_f32 v[74:75], v[42:43], v[190:191], v[74:75]
	s_waitcnt vmcnt(8)
	v_pk_fma_f32 v[72:73], v[40:41], v[176:177], v[72:73]
	v_pk_fma_f32 v[70:71], v[38:39], v[178:179], v[70:71]
	v_pk_mul_f32 v[44:45], v[186:187], v[80:81]
	v_pk_mul_f32 v[42:43], v[188:189], v[78:79]
	v_pk_mul_f32 v[82:83], v[182:183], v[76:77]
	v_pk_mul_f32 v[84:85], v[184:185], v[74:75]
	v_pk_fma_f32 v[68:69], v[36:37], v[174:175], v[68:69]
	v_pk_fma_f32 v[66:67], v[34:35], v[172:173], v[66:67]
	v_pk_mul_f32 v[36:37], v[168:169], v[72:73]
	v_pk_mul_f32 v[34:35], v[170:171], v[70:71]
	v_cvt_pk_bf16_f32 v46, v78, v79
	v_cvt_pk_bf16_f32 v47, v80, v81
	v_cvt_pk_bf16_f32 v48, v74, v75
	v_cvt_pk_bf16_f32 v49, v76, v77
	v_cvt_pk_bf16_f32 v42, v42, v43
	v_cvt_pk_bf16_f32 v43, v44, v45
	v_cvt_pk_bf16_f32 v44, v84, v85
	v_cvt_pk_bf16_f32 v45, v82, v83
	v_cvt_pk_bf16_f32 v38, v70, v71
	v_cvt_pk_bf16_f32 v39, v72, v73
	v_cvt_pk_bf16_f32 v40, v66, v67
	v_cvt_pk_bf16_f32 v41, v68, v69
	v_pk_mul_f32 v[82:83], v[164:165], v[68:69]
	v_pk_mul_f32 v[84:85], v[166:167], v[66:67]
	v_cvt_pk_bf16_f32 v34, v34, v35
	v_cvt_pk_bf16_f32 v35, v36, v37
	s_nop 0
	v_cvt_pk_bf16_f32 v36, v84, v85
	v_cvt_pk_bf16_f32 v37, v82, v83
	s_and_saveexec_b64 s[40:41], vcc
	s_cbranch_execz .LBB0_344
	ds_write_b128 v229, v[46:49]
	ds_write_b128 v229, v[38:41] offset:64

; __device__ __forceinline__ u32x4 pack8(const f32x4 a, const f32x4 b) { u32x4 w; w.x = cvt_pk_bf16(a[0], a[1]); w.y = cvt_pk_bf16(a[2], a[3]); w.z = cvt_pk_bf16(b[0], b[1]); w.w = cvt_pk_bf16(b[2], b[3]); return w; }
;     __device__ __forceinline__ void operator()(const f32x4 (&acc)[2][2][4][2], const Unit& u, int wr, int wc, int fr, int fq) const {
;     ...
;         RES_LOAD(c16, c32, 0);
; #pragma unroll
;         for (int r = 0; r < 8; ++r) { const int ai = r >> 2, m = r & 3; const int row = EPI_ROW; float sq = 0.f;
;             if (r < 7) RES_LOAD(n16, n32, r + 1);
;             u32x4 pn_[2], ps_[2];
; #pragma unroll
;             for (int bj = 0; bj < 2; ++bj) {
;                 f32x4 o0, o1;
;                 if (XOLD16) unpack8(c16[bj], o0, o1); else { o0 = c32[bj][0]; o1 = c32[bj][1]; }
;                 const f32x4 v0 = o0 + gv[bj][0] * acc[ai][bj][m][0], v1 = o1 + gv[bj][1] * acc[ai][bj][m][1];
;                 pn_[bj] = pack8(v0, v1);
;                 sq += ((v0[0] * v0[0] + v0[1] * v0[1]) + (v0[2] * v0[2] + v0[3] * v0[3])) + ((v1[0] * v1[0] + v1[1] * v1[1]) + (v1[2] * v1[2] + v1[3] * v1[3]));
;                 if (XS) ps_[bj] = pack8(v0 * cs[bj][0], v1 * cs[bj][1]); }
;             { const size_t seg = (size_t)(row - fr) * DM + u.pn * BM + wc * 64;
;               store_lines(st, pn_[0], pn_[1], fr, fq, xnew + seg, DM);
;               if (XS) store_lines(st, ps_[0], ps_[1], fr, fq, xs + seg, DM); }
.LBB0_352:
	s_or_b64 exec, exec, s[42:43]
	v_add_u32_e32 v34, 0xb0, v202
	s_waitcnt lgkmcnt(0)
	v_ashrrev_i32_e32 v35, 31, v34
	v_lshlrev_b64 v[34:35], 12, v[34:35]
	v_lshl_add_u64 v[34:35], s[10:11], 0, v[34:35]
	v_lshl_add_u64 v[38:39], v[200:201], 2, v[34:35]
	global_load_dwordx4 v[42:45], v[38:39], off offset:16 nt
	global_load_dwordx4 v[46:49], v[38:39], off nt
	global_load_dwordx4 v[34:37], v[38:39], off offset:144 nt
	s_nop 0
	global_load_dwordx4 v[38:41], v[38:39], off offset:128 nt
	s_waitcnt vmcnt(10)
	v_pk_fma_f32 v[64:65], v[32:33], v[194:195], v[64:65]
	v_pk_fma_f32 v[62:63], v[30:31], v[196:197], v[62:63]
	v_pk_fma_f32 v[60:61], v[28:29], v[192:193], v[60:61]
	v_pk_fma_f32 v[58:59], v[26:27], v[190:191], v[58:59]
	s_waitcnt vmcnt(8)
	v_pk_fma_f32 v[56:57], v[24:25], v[176:177], v[56:57]
	v_pk_fma_f32 v[54:55], v[22:23], v[178:179], v[54:55]
	v_pk_mul_f32 v[28:29], v[186:187], v[64:65]
	v_pk_mul_f32 v[26:27], v[188:189], v[62:63]
	v_pk_mul_f32 v[66:67], v[182:183], v[60:61]
	v_pk_mul_f32 v[68:69], v[184:185], v[58:59]
	v_pk_fma_f32 v[52:53], v[20:21], v[174:175], v[52:53]
	v_pk_fma_f32 v[50:51], v[18:19], v[172:173], v[50:51]
	v_pk_mul_f32 v[20:21], v[168:169], v[56:57]
	v_pk_mul_f32 v[18:19], v[170:171], v[54:55]
	v_cvt_pk_bf16_f32 v30, v62, v63
	v_cvt_pk_bf16_f32 v31, v64, v65
	v_cvt_pk_bf16_f32 v32, v58, v59
	v_cvt_pk_bf16_f32 v33, v60, v61
	v_cvt_pk_bf16_f32 v26, v26, v27
	v_cvt_pk_bf16_f32 v27, v28, v29
	v_cvt_pk_bf16_f32 v28, v68, v69
	v_cvt_pk_bf16_f32 v29, v66, v67
	v_cvt_pk_bf16_f32 v22, v54, v55
	v_cvt_pk_bf16_f32 v23, v56, v57
	v_cvt_pk_bf16_f32 v24, v50, v51
	v_cvt_pk_bf16_f32 v25, v52, v53
	v_pk_mul_f32 v[66:67], v[164:165], v[52:53]
	v_pk_mul_f32 v[68:69], v[166:167], v[50:51]
	v_cvt_pk_bf16_f32 v18, v18, v19
	v_cvt_pk_bf16_f32 v19, v20, v21
	s_nop 0
	v_cvt_pk_bf16_f32 v20, v68, v69
	v_cvt_pk_bf16_f32 v21, v66, v67
	s_and_saveexec_b64 s[40:41], vcc
	s_cbranch_execz .LBB0_354
	ds_write_b128 v229, v[30:33]
	ds_write_b128 v229, v[22:25] offset:64

; #define PG8_LAS __attribute__((address_space(3)))
; __device__ __forceinline__ u32x4 pack8(const f32x4 a, const f32x4 b) { u32x4 w; w.x = cvt_pk_bf16(a[0], a[1]); w.y = cvt_pk_bf16(a[2], a[3]); w.z = cvt_pk_bf16(b[0], b[1]); w.w = cvt_pk_bf16(b[2], b[3]); return w; }
;     __device__ __forceinline__ void operator()(const f32x4 (&acc)[2][2][4][2], const Unit& u, int wr, int wc, int fr, int fq) const {
;     ...
;         const int b = u.pm >> 5, col0 = u.pn * BM + wc * 64 + fq * 8;
;         PG8_LAS unsigned char* st = stg + (wr * 4 + wc) * 1024;
;         f32x4 gv[2][2], cs[2][2];
; #pragma unroll
;         for (int bj = 0; bj < 2; ++bj)
; #pragma unroll
;             for (int n = 0; n < 2; ++n) { const int c = col0 + bj * 32 + 4 * n; gv[bj][n] = *(const f32x4*)(gate + (size_t)b * NMODC + c) * (HALFG ? 0.5f : 1.0f);
;                 cs[bj][n] = (f32x4){0.f, 0.f, 0.f, 0.f}; if (XS) cs[bj][n] = *(const f32x4*)(gcol + c) * (*(const f32x4*)(scm + (size_t)b * NMODC + c) + 1.0f); }
;         u32x4 c16[2], n16[2]; f32x4 c32[2][2], n32[2][2];
;     ...
;         RES_LOAD(c16, c32, 0);
; #pragma unroll
;         for (int r = 0; r < 8; ++r) { const int ai = r >> 2, m = r & 3; const int row = EPI_ROW; float sq = 0.f;
;             if (r < 7) RES_LOAD(n16, n32, r + 1);
;             u32x4 pn_[2], ps_[2];
; #pragma unroll
;             for (int bj = 0; bj < 2; ++bj) {
;                 f32x4 o0, o1;
;                 if (XOLD16) unpack8(c16[bj], o0, o1); else { o0 = c32[bj][0]; o1 = c32[bj][1]; }
;                 const f32x4 v0 = o0 + gv[bj][0] * acc[ai][bj][m][0], v1 = o1 + gv[bj][1] * acc[ai][bj][m][1];
;                 pn_[bj] = pack8(v0, v1);
;                 sq += ((v0[0] * v0[0] + v0[1] * v0[1]) + (v0[2] * v0[2] + v0[3] * v0[3])) + ((v1[0] * v1[0] + v1[1] * v1[1]) + (v1[2] * v1[2] + v1[3] * v1[3]));
;                 if (XS) ps_[bj] = pack8(v0 * cs[bj][0], v1 * cs[bj][1]); }
;             { const size_t seg = (size_t)(row - fr) * DM + u.pn * BM + wc * 64;
;               store_lines(st, pn_[0], pn_[1], fr, fq, xnew + seg, DM);
;               if (XS) store_lines(st, ps_[0], ps_[1], fr, fq, xs + seg, DM); }
;             sq += __shfl_xor(sq, 16); sq += __shfl_xor(sq, 32);
;             if (fq == 0) ssq[(size_t)row * 16 + u.pn * 4 + wc] = sq;
.LBB0_841:
	s_mov_b32 s98, s0
	s_lshl_b32 s1, s14, 8
	s_or_b32 s1, s1, s24
	s_lshl_b32 s4, s98, 8
	s_add_i32 s4, s4, s62
	s_ashr_i32 s5, s98, 5
	s_mul_i32 s5, s5, 0x9000
	s_lshl_b32 s6, s1, 2
	s_add_u32 s5, s5, s6
	s_add_u32 s36, s55, s5
	s_addc_u32 s37, s56, 0
	s_add_u32 s38, s59, s5
	s_addc_u32 s39, s60, 0
	s_add_u32 s40, s10, s6
	s_addc_u32 s41, s11, 0
	v_lshlrev_b32_e32 v150, 5, v212
	global_load_dwordx4 v[184:187], v150, s[36:37] nt
	global_load_dwordx4 v[180:183], v150, s[36:37] offset:16 nt
	global_load_dwordx4 v[176:179], v150, s[36:37] offset:128 nt
	global_load_dwordx4 v[172:175], v150, s[36:37] offset:144 nt
	global_load_dwordx4 v[200:203], v150, s[38:39] nt
	global_load_dwordx4 v[196:199], v150, s[38:39] offset:16 nt
	global_load_dwordx4 v[192:195], v150, s[38:39] offset:128 nt
	global_load_dwordx4 v[188:191], v150, s[38:39] offset:144 nt
	global_load_dwordx4 v[236:239], v150, s[40:41] nt
	global_load_dwordx4 v[232:235], v150, s[40:41] offset:16 nt
	global_load_dwordx4 v[228:231], v150, s[40:41] offset:128 nt
	global_load_dwordx4 v[224:227], v150, s[40:41] offset:144 nt
	s_lshl_b32 s5, s4, 11
	s_lshl_b32 s6, s1, 1
	s_add_u32 s5, s5, s6
	s_add_u32 s36, s12, s5
	s_addc_u32 s37, s13, 0
	s_add_u32 s38, s100, s5
	s_addc_u32 s39, s101, 0
	s_add_u32 s40, s57, s5
	s_addc_u32 s41, s58, 0
	v_lshlrev_b32_e32 v151, 11, v1
	v_lshl_add_u32 v151, v212, 4, v151
	global_load_dwordx4 v[240:243], v151, s[36:37] nt
	global_load_dwordx4 v[244:247], v151, s[36:37] offset:64 nt
	s_add_u32 s36, s36, 0x8000
	s_addc_u32 s37, s37, 0
	global_load_dwordx4 v[248:251], v151, s[36:37] nt
	global_load_dwordx4 v[204:207], v151, s[36:37] offset:64 nt
	s_add_u32 s36, s36, 0x8000
	s_addc_u32 s37, s37, 0
	global_load_dwordx4 v[50:53], v151, s[36:37] nt
	global_load_dwordx4 v[54:57], v151, s[36:37] offset:64 nt
	s_add_u32 s36, s36, 0x8000
	s_addc_u32 s37, s37, 0
	v_lshlrev_b32_e32 v152, 6, v1
	s_lshl_b32 s5, s62, 7
	s_lshl_b32 s6, s61, 11
	s_add_i32 s5, s5, s6
	s_add_i32 s5, s5, 0x20000
	v_lshlrev_b32_e32 v153, 7, v1
	v_lshl_add_u32 v153, v212, 4, v153
	v_add_u32_e32 v153, s5, v153
	v_lshl_add_u32 v162, v217, 4, s5
	v_lshrrev_b32_e32 v255, 3, v217
	v_lshlrev_b32_e32 v255, 11, v255
	v_and_b32_e32 v208, 7, v217
	v_lshl_add_u32 v255, v208, 4, v255
	s_waitcnt vmcnt(6)
	v_pk_add_f32 v[188:189], v[188:189], 1.0 op_sel_hi:[1,0]
	v_pk_add_f32 v[190:191], v[190:191], 1.0 op_sel_hi:[1,0]
	v_pk_add_f32 v[192:193], v[192:193], 1.0 op_sel_hi:[1,0]
	v_pk_add_f32 v[194:195], v[194:195], 1.0 op_sel_hi:[1,0]
	v_pk_add_f32 v[196:197], v[196:197], 1.0 op_sel_hi:[1,0]
	v_pk_add_f32 v[198:199], v[198:199], 1.0 op_sel_hi:[1,0]
	v_pk_add_f32 v[200:201], v[200:201], 1.0 op_sel_hi:[1,0]
	v_pk_add_f32 v[202:203], v[202:203], 1.0 op_sel_hi:[1,0]
	v_pk_mul_f32 v[188:189], v[224:225], v[188:189]
	v_pk_mul_f32 v[190:191], v[226:227], v[190:191]
	v_pk_mul_f32 v[192:193], v[228:229], v[192:193]
	v_pk_mul_f32 v[194:195], v[230:231], v[194:195]
	v_pk_mul_f32 v[196:197], v[232:233], v[196:197]
	v_pk_mul_f32 v[198:199], v[234:235], v[198:199]
	v_pk_mul_f32 v[200:201], v[236:237], v[200:201]
	v_pk_mul_f32 v[202:203], v[238:239], v[202:203]
	s_waitcnt vmcnt(4)
	v_lshlrev_b32_e32 v236, 16, v240
	v_and_b32_e32 v237, 0xffff0000, v240
	v_lshlrev_b32_e32 v238, 16, v241
	v_and_b32_e32 v239, 0xffff0000, v241
	v_lshlrev_b32_e32 v232, 16, v242
	v_and_b32_e32 v233, 0xffff0000, v242
	v_lshlrev_b32_e32 v234, 16, v243
	v_and_b32_e32 v235, 0xffff0000, v243
	v_lshlrev_b32_e32 v228, 16, v244
	v_and_b32_e32 v229, 0xffff0000, v244
	v_lshlrev_b32_e32 v230, 16, v245
	v_and_b32_e32 v231, 0xffff0000, v245
	v_lshlrev_b32_e32 v224, 16, v246
	v_and_b32_e32 v225, 0xffff0000, v246
	v_lshlrev_b32_e32 v226, 16, v247
	v_and_b32_e32 v227, 0xffff0000, v247
	global_load_dwordx4 v[240:243], v151, s[36:37] nt
	global_load_dwordx4 v[244:247], v151, s[36:37] offset:64 nt
	s_add_u32 s36, s36, 0x28000
	s_addc_u32 s37, s37, 0
	v_pk_fma_f32 v[142:143], v[142:143], v[184:185], v[236:237]
	v_pk_fma_f32 v[144:145], v[144:145], v[186:187], v[238:239]
	v_pk_fma_f32 v[138:139], v[138:139], v[180:181], v[232:233]
	v_pk_fma_f32 v[140:141], v[140:141], v[182:183], v[234:235]
	v_pk_fma_f32 v[134:135], v[134:135], v[176:177], v[228:229]
	v_pk_fma_f32 v[136:137], v[136:137], v[178:179], v[230:231]
	v_pk_fma_f32 v[130:131], v[130:131], v[172:173], v[224:225]
	v_pk_fma_f32 v[132:133], v[132:133], v[174:175], v[226:227]
	v_mul_f32_e32 v224, v143, v143
	v_mul_f32_e32 v225, v145, v145
	v_fmac_f32_e32 v224, v142, v142
	v_fmac_f32_e32 v225, v144, v144
	v_add_f32_e32 v224, v224, v225
	v_mul_f32_e32 v225, v139, v139
	v_mul_f32_e32 v226, v141, v141
	v_fmac_f32_e32 v225, v138, v138
	v_fmac_f32_e32 v226, v140, v140
	v_add_f32_e32 v225, v225, v226
	v_add_f32_e32 v224, v224, v225
	v_mul_f32_e32 v225, v135, v135
	v_mul_f32_e32 v226, v137, v137
	v_fmac_f32_e32 v225, v134, v134
	v_fmac_f32_e32 v226, v136, v136
	v_add_f32_e32 v225, v225, v226
	v_mul_f32_e32 v226, v131, v131
	v_mul_f32_e32 v227, v133, v133
	v_fmac_f32_e32 v226, v130, v130
	v_fmac_f32_e32 v227, v132, v132
	v_add_f32_e32 v226, v226, v227
	v_add_f32_e32 v225, v225, v226
	v_add_f32_e32 v218, v224, v225
	v_cvt_pk_bf16_f32 v66, v142, v143
	v_cvt_pk_bf16_f32 v67, v144, v145
	v_cvt_pk_bf16_f32 v68, v138, v139
	v_cvt_pk_bf16_f32 v69, v140, v141
	v_cvt_pk_bf16_f32 v70, v134, v135
	v_cvt_pk_bf16_f32 v71, v136, v137
	v_cvt_pk_bf16_f32 v72, v130, v131
	v_cvt_pk_bf16_f32 v73, v132, v133
	ds_write_b128 v153, v[66:69]
	ds_write_b128 v153, v[70:73] offset:64
	ds_read_b128 v[208:211], v162
	ds_read_b128 v[146:149], v162 offset:1024
	s_add_u32 s4, s38, 0x4000
	s_addc_u32 s5, s39, 0
	s_waitcnt lgkmcnt(1)
; __device__ __forceinline__ u32x4 pack8(const f32x4 a, const f32x4 b) { u32x4 w; w.x = cvt_pk_bf16(a[0], a[1]); w.y = cvt_pk_bf16(a[2], a[3]); w.z = cvt_pk_bf16(b[0], b[1]); w.w = cvt_pk_bf16(b[2], b[3]); return w; }
;     __device__ __forceinline__ void operator()(const f32x4 (&acc)[2][2][4][2], const Unit& u, int wr, int wc, int fr, int fq) const {
;     ...
;         RES_LOAD(c16, c32, 0);
; #pragma unroll
;         for (int r = 0; r < 8; ++r) { const int ai = r >> 2, m = r & 3; const int row = EPI_ROW; float sq = 0.f;
;             if (r < 7) RES_LOAD(n16, n32, r + 1);
;             u32x4 pn_[2], ps_[2];
; #pragma unroll
;             for (int bj = 0; bj < 2; ++bj) {
;                 f32x4 o0, o1;
;                 if (XOLD16) unpack8(c16[bj], o0, o1); else { o0 = c32[bj][0]; o1 = c32[bj][1]; }
;                 const f32x4 v0 = o0 + gv[bj][0] * acc[ai][bj][m][0], v1 = o1 + gv[bj][1] * acc[ai][bj][m][1];
;                 pn_[bj] = pack8(v0, v1);
;                 sq += ((v0[0] * v0[0] + v0[1] * v0[1]) + (v0[2] * v0[2] + v0[3] * v0[3])) + ((v1[0] * v1[0] + v1[1] * v1[1]) + (v1[2] * v1[2] + v1[3] * v1[3]));
;                 if (XS) ps_[bj] = pack8(v0 * cs[bj][0], v1 * cs[bj][1]); }
;             { const size_t seg = (size_t)(row - fr) * DM + u.pn * BM + wc * 64;
;               store_lines(st, pn_[0], pn_[1], fr, fq, xnew + seg, DM);
;               if (XS) store_lines(st, ps_[0], ps_[1], fr, fq, xs + seg, DM); }
;             sq += __shfl_xor(sq, 16); sq += __shfl_xor(sq, 32);
;             if (fq == 0) ssq[(size_t)row * 16 + u.pn * 4 + wc] = sq;
	global_store_dwordx4 v255, v[208:211], s[38:39]
	s_waitcnt lgkmcnt(0)
	global_store_dwordx4 v255, v[146:149], s[4:5]
	v_pk_mul_f32 v[236:237], v[200:201], v[142:143]
	v_pk_mul_f32 v[238:239], v[202:203], v[144:145]
	v_pk_mul_f32 v[232:233], v[196:197], v[138:139]
	v_pk_mul_f32 v[234:235], v[198:199], v[140:141]
	v_pk_mul_f32 v[228:229], v[192:193], v[134:135]
	v_pk_mul_f32 v[230:231], v[194:195], v[136:137]
	v_pk_mul_f32 v[224:225], v[188:189], v[130:131]
	v_pk_mul_f32 v[226:227], v[190:191], v[132:133]
	v_cvt_pk_bf16_f32 v66, v236, v237
	v_cvt_pk_bf16_f32 v67, v238, v239
	v_cvt_pk_bf16_f32 v68, v232, v233
	v_cvt_pk_bf16_f32 v69, v234, v235
	v_cvt_pk_bf16_f32 v70, v228, v229
	v_cvt_pk_bf16_f32 v71, v230, v231
	v_cvt_pk_bf16_f32 v72, v224, v225
	v_cvt_pk_bf16_f32 v73, v226, v227
	ds_write_b128 v153, v[66:69]
	ds_write_b128 v153, v[70:73] offset:64
	ds_read_b128 v[208:211], v162
	ds_read_b128 v[146:149], v162 offset:1024
	s_add_u32 s4, s40, 0x4000
	s_addc_u32 s5, s41, 0
	s_waitcnt lgkmcnt(1)
	global_store_dwordx4 v255, v[208:211], s[40:41]
	s_waitcnt lgkmcnt(0)
	global_store_dwordx4 v255, v[146:149], s[4:5]
	s_add_u32 s38, s38, 0x8000
	s_addc_u32 s39, s39, 0
	s_add_u32 s40, s40, 0x8000
	s_addc_u32 s41, s41, 0
	s_waitcnt vmcnt(8)
	v_lshlrev_b32_e32 v236, 16, v248
	v_and_b32_e32 v237, 0xffff0000, v248
	v_lshlrev_b32_e32 v238, 16, v249
	v_and_b32_e32 v239, 0xffff0000, v249
	v_lshlrev_b32_e32 v232, 16, v250
	v_and_b32_e32 v233, 0xffff0000, v250
	v_lshlrev_b32_e32 v234, 16, v251
	v_and_b32_e32 v235, 0xffff0000, v251
	v_lshlrev_b32_e32 v228, 16, v204
	v_and_b32_e32 v229, 0xffff0000, v204
	v_lshlrev_b32_e32 v230, 16, v205
	v_and_b32_e32 v231, 0xffff0000, v205
	v_lshlrev_b32_e32 v224, 16, v206
	v_and_b32_e32 v225, 0xffff0000, v206
	v_lshlrev_b32_e32 v226, 16, v207
	v_and_b32_e32 v227, 0xffff0000, v207
	global_load_dwordx4 v[248:251], v151, s[36:37] nt
	global_load_dwordx4 v[204:207], v151, s[36:37] offset:64 nt
	s_add_u32 s36, s36, 0x8000
	s_addc_u32 s37, s37, 0
	v_pk_fma_f32 v[126:127], v[126:127], v[184:185], v[236:237]
	v_pk_fma_f32 v[128:129], v[128:129], v[186:187], v[238:239]
	v_pk_fma_f32 v[122:123], v[122:123], v[180:181], v[232:233]
	v_pk_fma_f32 v[124:125], v[124:125], v[182:183], v[234:235]
	v_pk_fma_f32 v[118:119], v[118:119], v[176:177], v[228:229]
	v_pk_fma_f32 v[120:121], v[120:121], v[178:179], v[230:231]
	v_pk_fma_f32 v[114:115], v[114:115], v[172:173], v[224:225]
	v_pk_fma_f32 v[116:117], v[116:117], v[174:175], v[226:227]
	v_mul_f32_e32 v224, v127, v127
	v_mul_f32_e32 v225, v129, v129
	v_fmac_f32_e32 v224, v126, v126
	v_fmac_f32_e32 v225, v128, v128
	v_add_f32_e32 v224, v224, v225
	v_mul_f32_e32 v225, v123, v123
	v_mul_f32_e32 v226, v125, v125
	v_fmac_f32_e32 v225, v122, v122
	v_fmac_f32_e32 v226, v124, v124
	v_add_f32_e32 v225, v225, v226
	v_add_f32_e32 v224, v224, v225
	v_mul_f32_e32 v225, v119, v119
	v_mul_f32_e32 v226, v121, v121
	v_fmac_f32_e32 v225, v118, v118
	v_fmac_f32_e32 v226, v120, v120
	v_add_f32_e32 v225, v225, v226
	v_mul_f32_e32 v226, v115, v115
	v_mul_f32_e32 v227, v117, v117
	v_fmac_f32_e32 v226, v114, v114
	v_fmac_f32_e32 v227, v116, v116
	v_add_f32_e32 v226, v226, v227
	v_add_f32_e32 v225, v225, v226
	v_add_f32_e32 v219, v224, v225
	v_cvt_pk_bf16_f32 v66, v126, v127
	v_cvt_pk_bf16_f32 v67, v128, v129
	v_cvt_pk_bf16_f32 v68, v122, v123
	v_cvt_pk_bf16_f32 v69, v124, v125
	v_cvt_pk_bf16_f32 v70, v118, v119
	v_cvt_pk_bf16_f32 v71, v120, v121
	v_cvt_pk_bf16_f32 v72, v114, v115
	v_cvt_pk_bf16_f32 v73, v116, v117
	ds_write_b128 v153, v[66:69]
	ds_write_b128 v153, v[70:73] offset:64
	ds_read_b128 v[208:211], v162
	ds_read_b128 v[146:149], v162 offset:1024
	s_add_u32 s4, s38, 0x4000
	s_addc_u32 s5, s39, 0
	s_waitcnt lgkmcnt(1)
	global_store_dwordx4 v255, v[208:211], s[38:39]
	s_waitcnt lgkmcnt(0)
	global_store_dwordx4 v255, v[146:149], s[4:5]
	v_pk_mul_f32 v[236:237], v[200:201], v[126:127]
	v_pk_mul_f32 v[238:239], v[202:203], v[128:129]
	v_pk_mul_f32 v[232:233], v[196:197], v[122:123]
	v_pk_mul_f32 v[234:235], v[198:199], v[124:125]
	v_pk_mul_f32 v[228:229], v[192:193], v[118:119]
	v_pk_mul_f32 v[230:231], v[194:195], v[120:121]
	v_pk_mul_f32 v[224:225], v[188:189], v[114:115]
	v_pk_mul_f32 v[226:227], v[190:191], v[116:117]
	v_cvt_pk_bf16_f32 v66, v236, v237
	v_cvt_pk_bf16_f32 v67, v238, v239
	v_cvt_pk_bf16_f32 v68, v232, v233
	v_cvt_pk_bf16_f32 v69, v234, v235
	v_cvt_pk_bf16_f32 v70, v228, v229
	v_cvt_pk_bf16_f32 v71, v230, v231
	v_cvt_pk_bf16_f32 v72, v224, v225
	v_cvt_pk_bf16_f32 v73, v226, v227
	ds_write_b128 v153, v[66:69]
	ds_write_b128 v153, v[70:73] offset:64
	ds_read_b128 v[208:211], v162
	ds_read_b128 v[146:149], v162 offset:1024
	s_add_u32 s4, s40, 0x4000
	s_addc_u32 s5, s41, 0
	s_waitcnt lgkmcnt(1)
	global_store_dwordx4 v255, v[208:211], s[40:41]
	s_waitcnt lgkmcnt(0)
	global_store_dwordx4 v255, v[146:149], s[4:5]
	s_add_u32 s38, s38, 0x8000
	s_addc_u32 s39, s39, 0
	s_add_u32 s40, s40, 0x8000
	s_addc_u32 s41, s41, 0
	s_waitcnt vmcnt(12)
; __device__ __forceinline__ u32x4 pack8(const f32x4 a, const f32x4 b) { u32x4 w; w.x = cvt_pk_bf16(a[0], a[1]); w.y = cvt_pk_bf16(a[2], a[3]); w.z = cvt_pk_bf16(b[0], b[1]); w.w = cvt_pk_bf16(b[2], b[3]); return w; }
;     __device__ __forceinline__ void operator()(const f32x4 (&acc)[2][2][4][2], const Unit& u, int wr, int wc, int fr, int fq) const {
;     ...
;         RES_LOAD(c16, c32, 0);
; #pragma unroll
;         for (int r = 0; r < 8; ++r) { const int ai = r >> 2, m = r & 3; const int row = EPI_ROW; float sq = 0.f;
;             if (r < 7) RES_LOAD(n16, n32, r + 1);
;             u32x4 pn_[2], ps_[2];
; #pragma unroll
;             for (int bj = 0; bj < 2; ++bj) {
;                 f32x4 o0, o1;
;                 if (XOLD16) unpack8(c16[bj], o0, o1); else { o0 = c32[bj][0]; o1 = c32[bj][1]; }
;                 const f32x4 v0 = o0 + gv[bj][0] * acc[ai][bj][m][0], v1 = o1 + gv[bj][1] * acc[ai][bj][m][1];
;                 pn_[bj] = pack8(v0, v1);
;                 sq += ((v0[0] * v0[0] + v0[1] * v0[1]) + (v0[2] * v0[2] + v0[3] * v0[3])) + ((v1[0] * v1[0] + v1[1] * v1[1]) + (v1[2] * v1[2] + v1[3] * v1[3]));
;                 if (XS) ps_[bj] = pack8(v0 * cs[bj][0], v1 * cs[bj][1]); }
;             { const size_t seg = (size_t)(row - fr) * DM + u.pn * BM + wc * 64;
;               store_lines(st, pn_[0], pn_[1], fr, fq, xnew + seg, DM);
;               if (XS) store_lines(st, ps_[0], ps_[1], fr, fq, xs + seg, DM); }
;             sq += __shfl_xor(sq, 16); sq += __shfl_xor(sq, 32);
;             if (fq == 0) ssq[(size_t)row * 16 + u.pn * 4 + wc] = sq;
	v_lshlrev_b32_e32 v236, 16, v50
	v_and_b32_e32 v237, 0xffff0000, v50
	v_lshlrev_b32_e32 v238, 16, v51
	v_and_b32_e32 v239, 0xffff0000, v51
	v_lshlrev_b32_e32 v232, 16, v52
	v_and_b32_e32 v233, 0xffff0000, v52
	v_lshlrev_b32_e32 v234, 16, v53
	v_and_b32_e32 v235, 0xffff0000, v53
	v_lshlrev_b32_e32 v228, 16, v54
	v_and_b32_e32 v229, 0xffff0000, v54
	v_lshlrev_b32_e32 v230, 16, v55
	v_and_b32_e32 v231, 0xffff0000, v55
	v_lshlrev_b32_e32 v224, 16, v56
	v_and_b32_e32 v225, 0xffff0000, v56
	v_lshlrev_b32_e32 v226, 16, v57
	v_and_b32_e32 v227, 0xffff0000, v57
	global_load_dwordx4 v[50:53], v151, s[36:37] nt
	global_load_dwordx4 v[54:57], v151, s[36:37] offset:64 nt
	s_add_u32 s36, s36, 0x8000
	s_addc_u32 s37, s37, 0
	v_pk_fma_f32 v[110:111], v[110:111], v[184:185], v[236:237]
	v_pk_fma_f32 v[112:113], v[112:113], v[186:187], v[238:239]
	v_pk_fma_f32 v[106:107], v[106:107], v[180:181], v[232:233]
	v_pk_fma_f32 v[108:109], v[108:109], v[182:183], v[234:235]
	v_pk_fma_f32 v[102:103], v[102:103], v[176:177], v[228:229]
	v_pk_fma_f32 v[104:105], v[104:105], v[178:179], v[230:231]
	v_pk_fma_f32 v[98:99], v[98:99], v[172:173], v[224:225]
	v_pk_fma_f32 v[100:101], v[100:101], v[174:175], v[226:227]
	v_mul_f32_e32 v224, v111, v111
	v_mul_f32_e32 v225, v113, v113
	v_fmac_f32_e32 v224, v110, v110
	v_fmac_f32_e32 v225, v112, v112
	v_add_f32_e32 v224, v224, v225
	v_mul_f32_e32 v225, v107, v107
	v_mul_f32_e32 v226, v109, v109
	v_fmac_f32_e32 v225, v106, v106
	v_fmac_f32_e32 v226, v108, v108
	v_add_f32_e32 v225, v225, v226
	v_add_f32_e32 v224, v224, v225
	v_mul_f32_e32 v225, v103, v103
	v_mul_f32_e32 v226, v105, v105
	v_fmac_f32_e32 v225, v102, v102
	v_fmac_f32_e32 v226, v104, v104
	v_add_f32_e32 v225, v225, v226
	v_mul_f32_e32 v226, v99, v99
	v_mul_f32_e32 v227, v101, v101
	v_fmac_f32_e32 v226, v98, v98
	v_fmac_f32_e32 v227, v100, v100
	v_add_f32_e32 v226, v226, v227
	v_add_f32_e32 v225, v225, v226
	v_add_f32_e32 v221, v224, v225
	v_cvt_pk_bf16_f32 v66, v110, v111
	v_cvt_pk_bf16_f32 v67, v112, v113
	v_cvt_pk_bf16_f32 v68, v106, v107
	v_cvt_pk_bf16_f32 v69, v108, v109
	v_cvt_pk_bf16_f32 v70, v102, v103
	v_cvt_pk_bf16_f32 v71, v104, v105
	v_cvt_pk_bf16_f32 v72, v98, v99
	v_cvt_pk_bf16_f32 v73, v100, v101
	ds_write_b128 v153, v[66:69]
	ds_write_b128 v153, v[70:73] offset:64
	ds_read_b128 v[208:211], v162
	ds_read_b128 v[146:149], v162 offset:1024
	s_add_u32 s4, s38, 0x4000
	s_addc_u32 s5, s39, 0
	s_waitcnt lgkmcnt(1)
	global_store_dwordx4 v255, v[208:211], s[38:39]
	s_waitcnt lgkmcnt(0)
	global_store_dwordx4 v255, v[146:149], s[4:5]
	v_pk_mul_f32 v[236:237], v[200:201], v[110:111]
	v_pk_mul_f32 v[238:239], v[202:203], v[112:113]
	v_pk_mul_f32 v[232:233], v[196:197], v[106:107]
	v_pk_mul_f32 v[234:235], v[198:199], v[108:109]
	v_pk_mul_f32 v[228:229], v[192:193], v[102:103]
	v_pk_mul_f32 v[230:231], v[194:195], v[104:105]
	v_pk_mul_f32 v[224:225], v[188:189], v[98:99]
	v_pk_mul_f32 v[226:227], v[190:191], v[100:101]
	v_cvt_pk_bf16_f32 v66, v236, v237
	v_cvt_pk_bf16_f32 v67, v238, v239
	v_cvt_pk_bf16_f32 v68, v232, v233
	v_cvt_pk_bf16_f32 v69, v234, v235
	v_cvt_pk_bf16_f32 v70, v228, v229
	v_cvt_pk_bf16_f32 v71, v230, v231
	v_cvt_pk_bf16_f32 v72, v224, v225
	v_cvt_pk_bf16_f32 v73, v226, v227
	ds_write_b128 v153, v[66:69]
	ds_write_b128 v153, v[70:73] offset:64
	ds_read_b128 v[208:211], v162
	ds_read_b128 v[146:149], v162 offset:1024
	s_add_u32 s4, s40, 0x4000
	s_addc_u32 s5, s41, 0
	s_waitcnt lgkmcnt(1)
	global_store_dwordx4 v255, v[208:211], s[40:41]
	s_waitcnt lgkmcnt(0)
	global_store_dwordx4 v255, v[146:149], s[4:5]
	s_add_u32 s38, s38, 0x8000
	s_addc_u32 s39, s39, 0
	s_add_u32 s40, s40, 0x8000
	s_addc_u32 s41, s41, 0
	s_waitcnt vmcnt(16)
	v_lshlrev_b32_e32 v236, 16, v240
	v_and_b32_e32 v237, 0xffff0000, v240
	v_lshlrev_b32_e32 v238, 16, v241
	v_and_b32_e32 v239, 0xffff0000, v241
	v_lshlrev_b32_e32 v232, 16, v242
	v_and_b32_e32 v233, 0xffff0000, v242
	v_lshlrev_b32_e32 v234, 16, v243
	v_and_b32_e32 v235, 0xffff0000, v243
	v_lshlrev_b32_e32 v228, 16, v244
	v_and_b32_e32 v229, 0xffff0000, v244
	v_lshlrev_b32_e32 v230, 16, v245
	v_and_b32_e32 v231, 0xffff0000, v245
	v_lshlrev_b32_e32 v224, 16, v246
	v_and_b32_e32 v225, 0xffff0000, v246
	v_lshlrev_b32_e32 v226, 16, v247
	v_and_b32_e32 v227, 0xffff0000, v247
	global_load_dwordx4 v[240:243], v151, s[36:37] nt
	global_load_dwordx4 v[244:247], v151, s[36:37] offset:64 nt
	s_add_u32 s36, s36, 0x8000
	s_addc_u32 s37, s37, 0
	v_pk_fma_f32 v[94:95], v[94:95], v[184:185], v[236:237]
	v_pk_fma_f32 v[96:97], v[96:97], v[186:187], v[238:239]
	v_pk_fma_f32 v[90:91], v[90:91], v[180:181], v[232:233]
	v_pk_fma_f32 v[92:93], v[92:93], v[182:183], v[234:235]
	v_pk_fma_f32 v[86:87], v[86:87], v[176:177], v[228:229]
	v_pk_fma_f32 v[88:89], v[88:89], v[178:179], v[230:231]
	v_pk_fma_f32 v[82:83], v[82:83], v[172:173], v[224:225]
	v_pk_fma_f32 v[84:85], v[84:85], v[174:175], v[226:227]
	v_mul_f32_e32 v224, v95, v95
	v_mul_f32_e32 v225, v97, v97
	v_fmac_f32_e32 v224, v94, v94
	v_fmac_f32_e32 v225, v96, v96
	v_add_f32_e32 v224, v224, v225
	v_mul_f32_e32 v225, v91, v91
	v_mul_f32_e32 v226, v93, v93
	v_fmac_f32_e32 v225, v90, v90
	v_fmac_f32_e32 v226, v92, v92
	v_add_f32_e32 v225, v225, v226
	v_add_f32_e32 v224, v224, v225
	v_mul_f32_e32 v225, v87, v87
	v_mul_f32_e32 v226, v89, v89
	v_fmac_f32_e32 v225, v86, v86
	v_fmac_f32_e32 v226, v88, v88
	v_add_f32_e32 v225, v225, v226
	v_mul_f32_e32 v226, v83, v83
	v_mul_f32_e32 v227, v85, v85
	v_fmac_f32_e32 v226, v82, v82
	v_fmac_f32_e32 v227, v84, v84
	v_add_f32_e32 v226, v226, v227
	v_add_f32_e32 v225, v225, v226
	v_add_f32_e32 v222, v224, v225
	v_cvt_pk_bf16_f32 v66, v94, v95
	v_cvt_pk_bf16_f32 v67, v96, v97
	v_cvt_pk_bf16_f32 v68, v90, v91
	v_cvt_pk_bf16_f32 v69, v92, v93
	v_cvt_pk_bf16_f32 v70, v86, v87
	v_cvt_pk_bf16_f32 v71, v88, v89
	v_cvt_pk_bf16_f32 v72, v82, v83
	v_cvt_pk_bf16_f32 v73, v84, v85
	ds_write_b128 v153, v[66:69]
	ds_write_b128 v153, v[70:73] offset:64
	ds_read_b128 v[208:211], v162
	ds_read_b128 v[146:149], v162 offset:1024
	s_add_u32 s4, s38, 0x4000
	s_addc_u32 s5, s39, 0
	s_waitcnt lgkmcnt(1)
; __device__ __forceinline__ u32x4 pack8(const f32x4 a, const f32x4 b) { u32x4 w; w.x = cvt_pk_bf16(a[0], a[1]); w.y = cvt_pk_bf16(a[2], a[3]); w.z = cvt_pk_bf16(b[0], b[1]); w.w = cvt_pk_bf16(b[2], b[3]); return w; }
;     __device__ __forceinline__ void operator()(const f32x4 (&acc)[2][2][4][2], const Unit& u, int wr, int wc, int fr, int fq) const {
;     ...
;         RES_LOAD(c16, c32, 0);
; #pragma unroll
;         for (int r = 0; r < 8; ++r) { const int ai = r >> 2, m = r & 3; const int row = EPI_ROW; float sq = 0.f;
;             if (r < 7) RES_LOAD(n16, n32, r + 1);
;             u32x4 pn_[2], ps_[2];
; #pragma unroll
;             for (int bj = 0; bj < 2; ++bj) {
;                 f32x4 o0, o1;
;                 if (XOLD16) unpack8(c16[bj], o0, o1); else { o0 = c32[bj][0]; o1 = c32[bj][1]; }
;                 const f32x4 v0 = o0 + gv[bj][0] * acc[ai][bj][m][0], v1 = o1 + gv[bj][1] * acc[ai][bj][m][1];
;                 pn_[bj] = pack8(v0, v1);
;                 sq += ((v0[0] * v0[0] + v0[1] * v0[1]) + (v0[2] * v0[2] + v0[3] * v0[3])) + ((v1[0] * v1[0] + v1[1] * v1[1]) + (v1[2] * v1[2] + v1[3] * v1[3]));
;                 if (XS) ps_[bj] = pack8(v0 * cs[bj][0], v1 * cs[bj][1]); }
;             { const size_t seg = (size_t)(row - fr) * DM + u.pn * BM + wc * 64;
;               store_lines(st, pn_[0], pn_[1], fr, fq, xnew + seg, DM);
;               if (XS) store_lines(st, ps_[0], ps_[1], fr, fq, xs + seg, DM); }
;             sq += __shfl_xor(sq, 16); sq += __shfl_xor(sq, 32);
;             if (fq == 0) ssq[(size_t)row * 16 + u.pn * 4 + wc] = sq;
	global_store_dwordx4 v255, v[208:211], s[38:39]
	s_waitcnt lgkmcnt(0)
	global_store_dwordx4 v255, v[146:149], s[4:5]
	v_pk_mul_f32 v[236:237], v[200:201], v[94:95]
	v_pk_mul_f32 v[238:239], v[202:203], v[96:97]
	v_pk_mul_f32 v[232:233], v[196:197], v[90:91]
	v_pk_mul_f32 v[234:235], v[198:199], v[92:93]
	v_pk_mul_f32 v[228:229], v[192:193], v[86:87]
	v_pk_mul_f32 v[230:231], v[194:195], v[88:89]
	v_pk_mul_f32 v[224:225], v[188:189], v[82:83]
	v_pk_mul_f32 v[226:227], v[190:191], v[84:85]
	v_cvt_pk_bf16_f32 v66, v236, v237
	v_cvt_pk_bf16_f32 v67, v238, v239
	v_cvt_pk_bf16_f32 v68, v232, v233
	v_cvt_pk_bf16_f32 v69, v234, v235
	v_cvt_pk_bf16_f32 v70, v228, v229
	v_cvt_pk_bf16_f32 v71, v230, v231
	v_cvt_pk_bf16_f32 v72, v224, v225
	v_cvt_pk_bf16_f32 v73, v226, v227
	ds_write_b128 v153, v[66:69]
	ds_write_b128 v153, v[70:73] offset:64
	ds_read_b128 v[208:211], v162
	ds_read_b128 v[146:149], v162 offset:1024
	s_add_u32 s4, s40, 0x4000
	s_addc_u32 s5, s41, 0
	s_waitcnt lgkmcnt(1)
	global_store_dwordx4 v255, v[208:211], s[40:41]
	s_waitcnt lgkmcnt(0)
	global_store_dwordx4 v255, v[146:149], s[4:5]
	s_add_u32 s38, s38, 0x28000
	s_addc_u32 s39, s39, 0
	s_add_u32 s40, s40, 0x28000
	s_addc_u32 s41, s41, 0
	s_waitcnt vmcnt(16)
	v_lshlrev_b32_e32 v236, 16, v248
	v_and_b32_e32 v237, 0xffff0000, v248
	v_lshlrev_b32_e32 v238, 16, v249
	v_and_b32_e32 v239, 0xffff0000, v249
	v_lshlrev_b32_e32 v232, 16, v250
	v_and_b32_e32 v233, 0xffff0000, v250
	v_lshlrev_b32_e32 v234, 16, v251
	v_and_b32_e32 v235, 0xffff0000, v251
	v_lshlrev_b32_e32 v228, 16, v204
	v_and_b32_e32 v229, 0xffff0000, v204
	v_lshlrev_b32_e32 v230, 16, v205
	v_and_b32_e32 v231, 0xffff0000, v205
	v_lshlrev_b32_e32 v224, 16, v206
	v_and_b32_e32 v225, 0xffff0000, v206
	v_lshlrev_b32_e32 v226, 16, v207
	v_and_b32_e32 v227, 0xffff0000, v207
	global_load_dwordx4 v[248:251], v151, s[36:37] nt
	global_load_dwordx4 v[204:207], v151, s[36:37] offset:64 nt
	v_pk_fma_f32 v[78:79], v[78:79], v[184:185], v[236:237]
	v_pk_fma_f32 v[80:81], v[80:81], v[186:187], v[238:239]
	v_pk_fma_f32 v[74:75], v[74:75], v[180:181], v[232:233]
	v_pk_fma_f32 v[76:77], v[76:77], v[182:183], v[234:235]
	v_pk_fma_f32 v[62:63], v[62:63], v[176:177], v[228:229]
	v_pk_fma_f32 v[64:65], v[64:65], v[178:179], v[230:231]
	v_pk_fma_f32 v[58:59], v[58:59], v[172:173], v[224:225]
	v_pk_fma_f32 v[60:61], v[60:61], v[174:175], v[226:227]
	v_mul_f32_e32 v224, v79, v79
	v_mul_f32_e32 v225, v81, v81
	v_fmac_f32_e32 v224, v78, v78
	v_fmac_f32_e32 v225, v80, v80
	v_add_f32_e32 v224, v224, v225
	v_mul_f32_e32 v225, v75, v75
	v_mul_f32_e32 v226, v77, v77
	v_fmac_f32_e32 v225, v74, v74
	v_fmac_f32_e32 v226, v76, v76
	v_add_f32_e32 v225, v225, v226
	v_add_f32_e32 v224, v224, v225
	v_mul_f32_e32 v225, v63, v63
	v_mul_f32_e32 v226, v65, v65
	v_fmac_f32_e32 v225, v62, v62
	v_fmac_f32_e32 v226, v64, v64
	v_add_f32_e32 v225, v225, v226
	v_mul_f32_e32 v226, v59, v59
	v_mul_f32_e32 v227, v61, v61
	v_fmac_f32_e32 v226, v58, v58
	v_fmac_f32_e32 v227, v60, v60
	v_add_f32_e32 v226, v226, v227
	v_add_f32_e32 v225, v225, v226
	v_add_f32_e32 v223, v224, v225
	v_cvt_pk_bf16_f32 v66, v78, v79
	v_cvt_pk_bf16_f32 v67, v80, v81
	v_cvt_pk_bf16_f32 v68, v74, v75
	v_cvt_pk_bf16_f32 v69, v76, v77
	v_cvt_pk_bf16_f32 v70, v62, v63
	v_cvt_pk_bf16_f32 v71, v64, v65
	v_cvt_pk_bf16_f32 v72, v58, v59
	v_cvt_pk_bf16_f32 v73, v60, v61
	ds_write_b128 v153, v[66:69]
	ds_write_b128 v153, v[70:73] offset:64
	ds_read_b128 v[208:211], v162
	ds_read_b128 v[146:149], v162 offset:1024
	s_add_u32 s4, s38, 0x4000
	s_addc_u32 s5, s39, 0
	s_waitcnt lgkmcnt(1)
	global_store_dwordx4 v255, v[208:211], s[38:39]
	s_waitcnt lgkmcnt(0)
	global_store_dwordx4 v255, v[146:149], s[4:5]
	v_pk_mul_f32 v[236:237], v[200:201], v[78:79]
	v_pk_mul_f32 v[238:239], v[202:203], v[80:81]
	v_pk_mul_f32 v[232:233], v[196:197], v[74:75]
	v_pk_mul_f32 v[234:235], v[198:199], v[76:77]
	v_pk_mul_f32 v[228:229], v[192:193], v[62:63]
	v_pk_mul_f32 v[230:231], v[194:195], v[64:65]
	v_pk_mul_f32 v[224:225], v[188:189], v[58:59]
	v_pk_mul_f32 v[226:227], v[190:191], v[60:61]
	v_cvt_pk_bf16_f32 v66, v236, v237
	v_cvt_pk_bf16_f32 v67, v238, v239
	v_cvt_pk_bf16_f32 v68, v232, v233
	v_cvt_pk_bf16_f32 v69, v234, v235
	v_cvt_pk_bf16_f32 v70, v228, v229
	v_cvt_pk_bf16_f32 v71, v230, v231
	v_cvt_pk_bf16_f32 v72, v224, v225
	v_cvt_pk_bf16_f32 v73, v226, v227
	ds_write_b128 v153, v[66:69]
	ds_write_b128 v153, v[70:73] offset:64
	ds_read_b128 v[208:211], v162
	ds_read_b128 v[146:149], v162 offset:1024
	s_add_u32 s4, s40, 0x4000
	s_addc_u32 s5, s41, 0
	s_waitcnt lgkmcnt(1)
	global_store_dwordx4 v255, v[208:211], s[40:41]
	s_waitcnt lgkmcnt(0)
	global_store_dwordx4 v255, v[146:149], s[4:5]
	s_add_u32 s38, s38, 0x8000
	s_addc_u32 s39, s39, 0
	s_add_u32 s40, s40, 0x8000
	s_addc_u32 s41, s41, 0
	s_waitcnt vmcnt(16)
; __device__ __forceinline__ u32x4 pack8(const f32x4 a, const f32x4 b) { u32x4 w; w.x = cvt_pk_bf16(a[0], a[1]); w.y = cvt_pk_bf16(a[2], a[3]); w.z = cvt_pk_bf16(b[0], b[1]); w.w = cvt_pk_bf16(b[2], b[3]); return w; }
;     __device__ __forceinline__ void operator()(const f32x4 (&acc)[2][2][4][2], const Unit& u, int wr, int wc, int fr, int fq) const {
;     ...
;         RES_LOAD(c16, c32, 0);
; #pragma unroll
;         for (int r = 0; r < 8; ++r) { const int ai = r >> 2, m = r & 3; const int row = EPI_ROW; float sq = 0.f;
;             if (r < 7) RES_LOAD(n16, n32, r + 1);
;             u32x4 pn_[2], ps_[2];
; #pragma unroll
;             for (int bj = 0; bj < 2; ++bj) {
;                 f32x4 o0, o1;
;                 if (XOLD16) unpack8(c16[bj], o0, o1); else { o0 = c32[bj][0]; o1 = c32[bj][1]; }
;                 const f32x4 v0 = o0 + gv[bj][0] * acc[ai][bj][m][0], v1 = o1 + gv[bj][1] * acc[ai][bj][m][1];
;                 pn_[bj] = pack8(v0, v1);
;                 sq += ((v0[0] * v0[0] + v0[1] * v0[1]) + (v0[2] * v0[2] + v0[3] * v0[3])) + ((v1[0] * v1[0] + v1[1] * v1[1]) + (v1[2] * v1[2] + v1[3] * v1[3]));
;                 if (XS) ps_[bj] = pack8(v0 * cs[bj][0], v1 * cs[bj][1]); }
;             { const size_t seg = (size_t)(row - fr) * DM + u.pn * BM + wc * 64;
;               store_lines(st, pn_[0], pn_[1], fr, fq, xnew + seg, DM);
;               if (XS) store_lines(st, ps_[0], ps_[1], fr, fq, xs + seg, DM); }
;             sq += __shfl_xor(sq, 16); sq += __shfl_xor(sq, 32);
;             if (fq == 0) ssq[(size_t)row * 16 + u.pn * 4 + wc] = sq;
	v_lshlrev_b32_e32 v236, 16, v50
	v_and_b32_e32 v237, 0xffff0000, v50
	v_lshlrev_b32_e32 v238, 16, v51
	v_and_b32_e32 v239, 0xffff0000, v51
	v_lshlrev_b32_e32 v232, 16, v52
	v_and_b32_e32 v233, 0xffff0000, v52
	v_lshlrev_b32_e32 v234, 16, v53
	v_and_b32_e32 v235, 0xffff0000, v53
	v_lshlrev_b32_e32 v228, 16, v54
	v_and_b32_e32 v229, 0xffff0000, v54
	v_lshlrev_b32_e32 v230, 16, v55
	v_and_b32_e32 v231, 0xffff0000, v55
	v_lshlrev_b32_e32 v224, 16, v56
	v_and_b32_e32 v225, 0xffff0000, v56
	v_lshlrev_b32_e32 v226, 16, v57
	v_and_b32_e32 v227, 0xffff0000, v57
	v_pk_fma_f32 v[46:47], v[46:47], v[184:185], v[236:237]
	v_pk_fma_f32 v[48:49], v[48:49], v[186:187], v[238:239]
	v_pk_fma_f32 v[42:43], v[42:43], v[180:181], v[232:233]
	v_pk_fma_f32 v[44:45], v[44:45], v[182:183], v[234:235]
	v_pk_fma_f32 v[38:39], v[38:39], v[176:177], v[228:229]
	v_pk_fma_f32 v[40:41], v[40:41], v[178:179], v[230:231]
	v_pk_fma_f32 v[34:35], v[34:35], v[172:173], v[224:225]
	v_pk_fma_f32 v[36:37], v[36:37], v[174:175], v[226:227]
	v_mul_f32_e32 v224, v47, v47
	v_mul_f32_e32 v225, v49, v49
	v_fmac_f32_e32 v224, v46, v46
	v_fmac_f32_e32 v225, v48, v48
	v_add_f32_e32 v224, v224, v225
	v_mul_f32_e32 v225, v43, v43
	v_mul_f32_e32 v226, v45, v45
	v_fmac_f32_e32 v225, v42, v42
	v_fmac_f32_e32 v226, v44, v44
	v_add_f32_e32 v225, v225, v226
	v_add_f32_e32 v224, v224, v225
	v_mul_f32_e32 v225, v39, v39
	v_mul_f32_e32 v226, v41, v41
	v_fmac_f32_e32 v225, v38, v38
	v_fmac_f32_e32 v226, v40, v40
	v_add_f32_e32 v225, v225, v226
	v_mul_f32_e32 v226, v35, v35
	v_mul_f32_e32 v227, v37, v37
	v_fmac_f32_e32 v226, v34, v34
	v_fmac_f32_e32 v227, v36, v36
	v_add_f32_e32 v226, v226, v227
	v_add_f32_e32 v225, v225, v226
	v_add_f32_e32 v252, v224, v225
	v_cvt_pk_bf16_f32 v66, v46, v47
	v_cvt_pk_bf16_f32 v67, v48, v49
	v_cvt_pk_bf16_f32 v68, v42, v43
	v_cvt_pk_bf16_f32 v69, v44, v45
	v_cvt_pk_bf16_f32 v70, v38, v39
	v_cvt_pk_bf16_f32 v71, v40, v41
	v_cvt_pk_bf16_f32 v72, v34, v35
	v_cvt_pk_bf16_f32 v73, v36, v37
	ds_write_b128 v153, v[66:69]
	ds_write_b128 v153, v[70:73] offset:64
	ds_read_b128 v[208:211], v162
	ds_read_b128 v[146:149], v162 offset:1024
	s_add_u32 s4, s38, 0x4000
	s_addc_u32 s5, s39, 0
	s_waitcnt lgkmcnt(1)
	global_store_dwordx4 v255, v[208:211], s[38:39]
	s_waitcnt lgkmcnt(0)
	global_store_dwordx4 v255, v[146:149], s[4:5]
	v_pk_mul_f32 v[236:237], v[200:201], v[46:47]
	v_pk_mul_f32 v[238:239], v[202:203], v[48:49]
	v_pk_mul_f32 v[232:233], v[196:197], v[42:43]
	v_pk_mul_f32 v[234:235], v[198:199], v[44:45]
	v_pk_mul_f32 v[228:229], v[192:193], v[38:39]
	v_pk_mul_f32 v[230:231], v[194:195], v[40:41]
	v_pk_mul_f32 v[224:225], v[188:189], v[34:35]
	v_pk_mul_f32 v[226:227], v[190:191], v[36:37]
	v_cvt_pk_bf16_f32 v66, v236, v237
	v_cvt_pk_bf16_f32 v67, v238, v239
	v_cvt_pk_bf16_f32 v68, v232, v233
	v_cvt_pk_bf16_f32 v69, v234, v235
	v_cvt_pk_bf16_f32 v70, v228, v229
	v_cvt_pk_bf16_f32 v71, v230, v231
	v_cvt_pk_bf16_f32 v72, v224, v225
	v_cvt_pk_bf16_f32 v73, v226, v227
	ds_write_b128 v153, v[66:69]
	ds_write_b128 v153, v[70:73] offset:64
	ds_read_b128 v[208:211], v162
	ds_read_b128 v[146:149], v162 offset:1024
	s_add_u32 s4, s40, 0x4000
	s_addc_u32 s5, s41, 0
	s_waitcnt lgkmcnt(1)
	global_store_dwordx4 v255, v[208:211], s[40:41]
	s_waitcnt lgkmcnt(0)
	global_store_dwordx4 v255, v[146:149], s[4:5]
	s_add_u32 s38, s38, 0x8000
	s_addc_u32 s39, s39, 0
	s_add_u32 s40, s40, 0x8000
	s_addc_u32 s41, s41, 0
	s_waitcnt vmcnt(14)
	v_lshlrev_b32_e32 v236, 16, v240
	v_and_b32_e32 v237, 0xffff0000, v240
	v_lshlrev_b32_e32 v238, 16, v241
	v_and_b32_e32 v239, 0xffff0000, v241
	v_lshlrev_b32_e32 v232, 16, v242
	v_and_b32_e32 v233, 0xffff0000, v242
	v_lshlrev_b32_e32 v234, 16, v243
	v_and_b32_e32 v235, 0xffff0000, v243
	v_lshlrev_b32_e32 v228, 16, v244
	v_and_b32_e32 v229, 0xffff0000, v244
	v_lshlrev_b32_e32 v230, 16, v245
	v_and_b32_e32 v231, 0xffff0000, v245
	v_lshlrev_b32_e32 v224, 16, v246
	v_and_b32_e32 v225, 0xffff0000, v246
	v_lshlrev_b32_e32 v226, 16, v247
	v_and_b32_e32 v227, 0xffff0000, v247
	v_pk_fma_f32 v[30:31], v[30:31], v[184:185], v[236:237]
	v_pk_fma_f32 v[32:33], v[32:33], v[186:187], v[238:239]
	v_pk_fma_f32 v[26:27], v[26:27], v[180:181], v[232:233]
	v_pk_fma_f32 v[28:29], v[28:29], v[182:183], v[234:235]
	v_pk_fma_f32 v[22:23], v[22:23], v[176:177], v[228:229]
	v_pk_fma_f32 v[24:25], v[24:25], v[178:179], v[230:231]
	v_pk_fma_f32 v[18:19], v[18:19], v[172:173], v[224:225]
	v_pk_fma_f32 v[20:21], v[20:21], v[174:175], v[226:227]
	v_mul_f32_e32 v224, v31, v31
	v_mul_f32_e32 v225, v33, v33
	v_fmac_f32_e32 v224, v30, v30
	v_fmac_f32_e32 v225, v32, v32
	v_add_f32_e32 v224, v224, v225
	v_mul_f32_e32 v225, v27, v27
	v_mul_f32_e32 v226, v29, v29
	v_fmac_f32_e32 v225, v26, v26
	v_fmac_f32_e32 v226, v28, v28
	v_add_f32_e32 v225, v225, v226
	v_add_f32_e32 v224, v224, v225
	v_mul_f32_e32 v225, v23, v23
	v_mul_f32_e32 v226, v25, v25
	v_fmac_f32_e32 v225, v22, v22
	v_fmac_f32_e32 v226, v24, v24
	v_add_f32_e32 v225, v225, v226
	v_mul_f32_e32 v226, v19, v19
	v_mul_f32_e32 v227, v21, v21
	v_fmac_f32_e32 v226, v18, v18
	v_fmac_f32_e32 v227, v20, v20
	v_add_f32_e32 v226, v226, v227
	v_add_f32_e32 v225, v225, v226
	v_add_f32_e32 v253, v224, v225
	v_cvt_pk_bf16_f32 v66, v30, v31
	v_cvt_pk_bf16_f32 v67, v32, v33
	v_cvt_pk_bf16_f32 v68, v26, v27
	v_cvt_pk_bf16_f32 v69, v28, v29
	v_cvt_pk_bf16_f32 v70, v22, v23
	v_cvt_pk_bf16_f32 v71, v24, v25
	v_cvt_pk_bf16_f32 v72, v18, v19
	v_cvt_pk_bf16_f32 v73, v20, v21
	ds_write_b128 v153, v[66:69]
	ds_write_b128 v153, v[70:73] offset:64
	ds_read_b128 v[208:211], v162
	ds_read_b128 v[146:149], v162 offset:1024
	s_add_u32 s4, s38, 0x4000
	s_addc_u32 s5, s39, 0
	s_waitcnt lgkmcnt(1)
; __device__ __forceinline__ u32x4 pack8(const f32x4 a, const f32x4 b) { u32x4 w; w.x = cvt_pk_bf16(a[0], a[1]); w.y = cvt_pk_bf16(a[2], a[3]); w.z = cvt_pk_bf16(b[0], b[1]); w.w = cvt_pk_bf16(b[2], b[3]); return w; }
;     __device__ __forceinline__ void operator()(const f32x4 (&acc)[2][2][4][2], const Unit& u, int wr, int wc, int fr, int fq) const {
;     ...
;                 sq += ((v0[0] * v0[0] + v0[1] * v0[1]) + (v0[2] * v0[2] + v0[3] * v0[3])) + ((v1[0] * v1[0] + v1[1] * v1[1]) + (v1[2] * v1[2] + v1[3] * v1[3]));
;                 if (XS) ps_[bj] = pack8(v0 * cs[bj][0], v1 * cs[bj][1]); }
;             { const size_t seg = (size_t)(row - fr) * DM + u.pn * BM + wc * 64;
;               store_lines(st, pn_[0], pn_[1], fr, fq, xnew + seg, DM);
;               if (XS) store_lines(st, ps_[0], ps_[1], fr, fq, xs + seg, DM); }
;             sq += __shfl_xor(sq, 16); sq += __shfl_xor(sq, 32);
;             if (fq == 0) ssq[(size_t)row * 16 + u.pn * 4 + wc] = sq;
; #pragma unroll
;             for (int bj = 0; bj < 2; ++bj) { c16[bj] = n16[bj]; c32[bj][0] = n32[bj][0]; c32[bj][1] = n32[bj][1]; } }
	global_store_dwordx4 v255, v[208:211], s[38:39]
	s_waitcnt lgkmcnt(0)
	global_store_dwordx4 v255, v[146:149], s[4:5]
	v_pk_mul_f32 v[236:237], v[200:201], v[30:31]
	v_pk_mul_f32 v[238:239], v[202:203], v[32:33]
	v_pk_mul_f32 v[232:233], v[196:197], v[26:27]
	v_pk_mul_f32 v[234:235], v[198:199], v[28:29]
	v_pk_mul_f32 v[228:229], v[192:193], v[22:23]
	v_pk_mul_f32 v[230:231], v[194:195], v[24:25]
	v_pk_mul_f32 v[224:225], v[188:189], v[18:19]
	v_pk_mul_f32 v[226:227], v[190:191], v[20:21]
	v_cvt_pk_bf16_f32 v66, v236, v237
	v_cvt_pk_bf16_f32 v67, v238, v239
	v_cvt_pk_bf16_f32 v68, v232, v233
	v_cvt_pk_bf16_f32 v69, v234, v235
	v_cvt_pk_bf16_f32 v70, v228, v229
	v_cvt_pk_bf16_f32 v71, v230, v231
	v_cvt_pk_bf16_f32 v72, v224, v225
	v_cvt_pk_bf16_f32 v73, v226, v227
	ds_write_b128 v153, v[66:69]
	ds_write_b128 v153, v[70:73] offset:64
	ds_read_b128 v[208:211], v162
	ds_read_b128 v[146:149], v162 offset:1024
	s_add_u32 s4, s40, 0x4000
	s_addc_u32 s5, s41, 0
	s_waitcnt lgkmcnt(1)
	global_store_dwordx4 v255, v[208:211], s[40:41]
	s_waitcnt lgkmcnt(0)
	global_store_dwordx4 v255, v[146:149], s[4:5]
	s_add_u32 s38, s38, 0x8000
	s_addc_u32 s39, s39, 0
	s_add_u32 s40, s40, 0x8000
	s_addc_u32 s41, s41, 0
	s_waitcnt vmcnt(12)
	v_lshlrev_b32_e32 v236, 16, v248
	v_and_b32_e32 v237, 0xffff0000, v248
	v_lshlrev_b32_e32 v238, 16, v249
	v_and_b32_e32 v239, 0xffff0000, v249
	v_lshlrev_b32_e32 v232, 16, v250
	v_and_b32_e32 v233, 0xffff0000, v250
	v_lshlrev_b32_e32 v234, 16, v251
	v_and_b32_e32 v235, 0xffff0000, v251
	v_lshlrev_b32_e32 v228, 16, v204
	v_and_b32_e32 v229, 0xffff0000, v204
	v_lshlrev_b32_e32 v230, 16, v205
	v_and_b32_e32 v231, 0xffff0000, v205
	v_lshlrev_b32_e32 v224, 16, v206
	v_and_b32_e32 v225, 0xffff0000, v206
	v_lshlrev_b32_e32 v226, 16, v207
	v_and_b32_e32 v227, 0xffff0000, v207
	v_pk_fma_f32 v[14:15], v[14:15], v[184:185], v[236:237]
	v_pk_fma_f32 v[16:17], v[16:17], v[186:187], v[238:239]
	v_pk_fma_f32 v[10:11], v[10:11], v[180:181], v[232:233]
	v_pk_fma_f32 v[12:13], v[12:13], v[182:183], v[234:235]
	v_pk_fma_f32 v[6:7], v[6:7], v[176:177], v[228:229]
	v_pk_fma_f32 v[8:9], v[8:9], v[178:179], v[230:231]
	v_pk_fma_f32 v[2:3], v[2:3], v[172:173], v[224:225]
	v_pk_fma_f32 v[4:5], v[4:5], v[174:175], v[226:227]
	v_mul_f32_e32 v224, v15, v15
	v_mul_f32_e32 v225, v17, v17
	v_fmac_f32_e32 v224, v14, v14
	v_fmac_f32_e32 v225, v16, v16
	v_add_f32_e32 v224, v224, v225
	v_mul_f32_e32 v225, v11, v11
	v_mul_f32_e32 v226, v13, v13
	v_fmac_f32_e32 v225, v10, v10
	v_fmac_f32_e32 v226, v12, v12
	v_add_f32_e32 v225, v225, v226
	v_add_f32_e32 v224, v224, v225
	v_mul_f32_e32 v225, v7, v7
	v_mul_f32_e32 v226, v9, v9
	v_fmac_f32_e32 v225, v6, v6
	v_fmac_f32_e32 v226, v8, v8
	v_add_f32_e32 v225, v225, v226
	v_mul_f32_e32 v226, v3, v3
	v_mul_f32_e32 v227, v5, v5
	v_fmac_f32_e32 v226, v2, v2
	v_fmac_f32_e32 v227, v4, v4
	v_add_f32_e32 v226, v226, v227
	v_add_f32_e32 v225, v225, v226
	v_add_f32_e32 v150, v224, v225
	v_cvt_pk_bf16_f32 v66, v14, v15
	v_cvt_pk_bf16_f32 v67, v16, v17
	v_cvt_pk_bf16_f32 v68, v10, v11
	v_cvt_pk_bf16_f32 v69, v12, v13
	v_cvt_pk_bf16_f32 v70, v6, v7
	v_cvt_pk_bf16_f32 v71, v8, v9
	v_cvt_pk_bf16_f32 v72, v2, v3
	v_cvt_pk_bf16_f32 v73, v4, v5
	ds_write_b128 v153, v[66:69]
	ds_write_b128 v153, v[70:73] offset:64
	ds_read_b128 v[208:211], v162
	ds_read_b128 v[146:149], v162 offset:1024
	s_add_u32 s4, s38, 0x4000
	s_addc_u32 s5, s39, 0
	s_waitcnt lgkmcnt(1)
	global_store_dwordx4 v255, v[208:211], s[38:39]
	s_waitcnt lgkmcnt(0)
	global_store_dwordx4 v255, v[146:149], s[4:5]
	v_pk_mul_f32 v[236:237], v[200:201], v[14:15]
	v_pk_mul_f32 v[238:239], v[202:203], v[16:17]
	v_pk_mul_f32 v[232:233], v[196:197], v[10:11]
	v_pk_mul_f32 v[234:235], v[198:199], v[12:13]
	v_pk_mul_f32 v[228:229], v[192:193], v[6:7]
	v_pk_mul_f32 v[230:231], v[194:195], v[8:9]
	v_pk_mul_f32 v[224:225], v[188:189], v[2:3]
	v_pk_mul_f32 v[226:227], v[190:191], v[4:5]
	v_cvt_pk_bf16_f32 v66, v236, v237
	v_cvt_pk_bf16_f32 v67, v238, v239
	v_cvt_pk_bf16_f32 v68, v232, v233
	v_cvt_pk_bf16_f32 v69, v234, v235
	v_cvt_pk_bf16_f32 v70, v228, v229
	v_cvt_pk_bf16_f32 v71, v230, v231
	v_cvt_pk_bf16_f32 v72, v224, v225
	v_cvt_pk_bf16_f32 v73, v226, v227
	ds_write_b128 v153, v[66:69]
	ds_write_b128 v153, v[70:73] offset:64
	ds_read_b128 v[208:211], v162
	ds_read_b128 v[146:149], v162 offset:1024
	s_add_u32 s4, s40, 0x4000
	s_addc_u32 s5, s41, 0
	s_waitcnt lgkmcnt(1)
	global_store_dwordx4 v255, v[208:211], s[40:41]
	s_waitcnt lgkmcnt(0)
	global_store_dwordx4 v255, v[146:149], s[4:5]
	v_xor_b32_e32 v208, 16, v217
	v_xor_b32_e32 v209, 32, v217
	v_lshlrev_b32_e32 v208, 2, v208
	v_lshlrev_b32_e32 v209, 2, v209
	ds_bpermute_b32 v66, v208, v218
	ds_bpermute_b32 v67, v208, v219
	ds_bpermute_b32 v68, v208, v221
	ds_bpermute_b32 v69, v208, v222
	ds_bpermute_b32 v70, v208, v223
	ds_bpermute_b32 v71, v208, v252
	ds_bpermute_b32 v72, v208, v253
	ds_bpermute_b32 v73, v208, v150
	s_waitcnt lgkmcnt(0)
	v_add_f32_e32 v218, v218, v66
	v_add_f32_e32 v219, v219, v67
	v_add_f32_e32 v221, v221, v68
	v_add_f32_e32 v222, v222, v69
	v_add_f32_e32 v223, v223, v70
	v_add_f32_e32 v252, v252, v71
	v_add_f32_e32 v253, v253, v72
	v_add_f32_e32 v150, v150, v73
	ds_bpermute_b32 v66, v209, v218
	ds_bpermute_b32 v67, v209, v219
	ds_bpermute_b32 v68, v209, v221
	ds_bpermute_b32 v69, v209, v222
	ds_bpermute_b32 v70, v209, v223
	ds_bpermute_b32 v71, v209, v252
	ds_bpermute_b32 v72, v209, v253
	ds_bpermute_b32 v73, v209, v150
	s_waitcnt lgkmcnt(0)
	v_add_f32_e32 v218, v218, v66
	v_add_f32_e32 v219, v219, v67
	v_add_f32_e32 v221, v221, v68
	v_add_f32_e32 v222, v222, v69
	v_add_f32_e32 v223, v223, v70
	v_add_f32_e32 v252, v252, v71
	v_add_f32_e32 v253, v253, v72
	v_add_f32_e32 v150, v150, v73
	s_lshl_b32 s4, s98, 8
	s_add_i32 s4, s4, s62
	s_lshl_b32 s4, s4, 6
	s_lshl_b32 s5, s14, 4
	s_add_u32 s4, s4, s5
	s_lshl_b32 s5, s61, 2
	s_add_u32 s4, s4, s5
	s_add_u32 s36, s18, s4
	s_addc_u32 s37, s19, 0
	s_add_u32 s38, s36, 0x2000
	s_addc_u32 s39, s37, 0
	s_mov_b64 exec, 0xffff
	global_store_dword v152, v218, s[36:37] offset:0
	global_store_dword v152, v219, s[36:37] offset:1024
	global_store_dword v152, v221, s[36:37] offset:2048
	global_store_dword v152, v222, s[36:37] offset:3072
	global_store_dword v152, v223, s[38:39] offset:0
	global_store_dword v152, v252, s[38:39] offset:1024
	global_store_dword v152, v253, s[38:39] offset:2048
	global_store_dword v152, v150, s[38:39] offset:3072
	s_mov_b64 exec, -1
	s_andn2_b64 vcc, exec, s[2:3]
	s_mov_b64 s[0:1], -1
	s_cbranch_vccnz .LBB0_830
	s_andn2_b64 vcc, exec, s[16:17]
	s_cbranch_vccnz .LBB0_829
	s_barrier
	s_branch .LBB0_829

; #define PG8_LAS __attribute__((address_space(3)))
;     __device__ __forceinline__ void operator()(const f32x4 (&acc)[2][2][4][2], const Unit& u, int wr, int wc, int fr, int fq) const {
;     ...
;         const int b = u.pm >> 5, col0 = u.pn * BM + wc * 64 + fq * 8;
;         PG8_LAS unsigned char* st = stg + (wr * 4 + wc) * 1024;
;         f32x4 gv[2][2], cs[2][2];
; #pragma unroll
;         for (int bj = 0; bj < 2; ++bj)
; #pragma unroll
;             for (int n = 0; n < 2; ++n) { const int c = col0 + bj * 32 + 4 * n; gv[bj][n] = *(const f32x4*)(gate + (size_t)b * NMODC + c) * (HALFG ? 0.5f : 1.0f);
;                 cs[bj][n] = (f32x4){0.f, 0.f, 0.f, 0.f}; if (XS) cs[bj][n] = *(const f32x4*)(gcol + c) * (*(const f32x4*)(scm + (size_t)b * NMODC + c) + 1.0f); }
;         u32x4 c16[2], n16[2]; f32x4 c32[2][2], n32[2][2];
;     ...
;         RES_LOAD(c16, c32, 0);
.LBB0_1072:
	s_mov_b32 s98, s34
	v_readlane_b32 s34, v254, 1
	v_readlane_b32 s35, v254, 2
	s_lshl_b32 s0, s10, 8
	s_or_b32 s0, s0, s57
	s_lshl_b32 s1, s98, 8
	s_add_i32 s1, s1, s54
	s_load_dwordx2 s[100:101], s[34:35], 0x88
	s_ashr_i32 s4, s98, 5
	s_mul_i32 s4, s4, 0x9000
	s_add_u32 s6, s51, s4
	s_addc_u32 s7, s52, 0
	s_lshl_b32 s4, s0, 2
	s_add_u32 s6, s6, s4
	s_addc_u32 s7, s7, 0
	v_lshlrev_b32_e32 v188, 5, v190
	global_load_dwordx4 v[168:171], v188, s[6:7] nt
	global_load_dwordx4 v[164:167], v188, s[6:7] offset:16 nt
	global_load_dwordx4 v[160:163], v188, s[6:7] offset:128 nt
	global_load_dwordx4 v[156:159], v188, s[6:7] offset:144 nt
	s_lshl_b32 s4, s1, 11
	s_lshl_b32 s5, s0, 1
	s_add_u32 s4, s4, s5
	s_add_u32 s36, s78, 0x18000000
	s_addc_u32 s37, s79, 0
	s_add_u32 s36, s36, s4
	s_addc_u32 s37, s37, 0
	v_lshlrev_b32_e32 v189, 11, v1
	v_lshl_add_u32 v189, v190, 4, v189
	global_load_dwordx4 v[196:199], v189, s[36:37] nt
	global_load_dwordx4 v[200:203], v189, s[36:37] offset:64 nt
	s_add_u32 s36, s36, 0x8000
	s_addc_u32 s37, s37, 0
	global_load_dwordx4 v[204:207], v189, s[36:37] nt
	global_load_dwordx4 v[208:211], v189, s[36:37] offset:64 nt
	s_add_u32 s36, s36, 0x8000
	s_addc_u32 s37, s37, 0
	global_load_dwordx4 v[212:215], v189, s[36:37] nt
	global_load_dwordx4 v[216:219], v189, s[36:37] offset:64 nt
	s_add_u32 s36, s36, 0x8000
	s_addc_u32 s37, s37, 0
	global_load_dwordx4 v[220:223], v189, s[36:37] nt
	global_load_dwordx4 v[224:227], v189, s[36:37] offset:64 nt
	s_add_u32 s36, s36, 0x28000
	s_addc_u32 s37, s37, 0
	global_load_dwordx4 v[228:231], v189, s[36:37] nt
	global_load_dwordx4 v[232:235], v189, s[36:37] offset:64 nt
	s_add_u32 s36, s36, 0x8000
	s_addc_u32 s37, s37, 0
	global_load_dwordx4 v[236:239], v189, s[36:37] nt
	global_load_dwordx4 v[240:243], v189, s[36:37] offset:64 nt
	s_add_u32 s36, s36, 0x8000
	s_addc_u32 s37, s37, 0
	global_load_dwordx4 v[244:247], v189, s[36:37] nt
	global_load_dwordx4 v[248:251], v189, s[36:37] offset:64 nt
	s_add_u32 s36, s36, 0x8000
	s_addc_u32 s37, s37, 0
	global_load_dwordx4 v[130:133], v189, s[36:37] nt
	global_load_dwordx4 v[134:137], v189, s[36:37] offset:64 nt
	v_xor_b32_e32 v255, 16, v195
	v_xor_b32_e32 v252, 32, v195
	v_lshlrev_b32_e32 v255, 2, v255
	v_lshlrev_b32_e32 v252, 2, v252
	v_lshlrev_b32_e32 v146, 6, v1
	s_waitcnt vmcnt(16)
	v_pk_mul_f32 v[156:157], v[156:157], 0.5 op_sel_hi:[1,0]
	v_pk_mul_f32 v[158:159], v[158:159], 0.5 op_sel_hi:[1,0]
	v_pk_mul_f32 v[160:161], v[160:161], 0.5 op_sel_hi:[1,0]
	v_pk_mul_f32 v[162:163], v[162:163], 0.5 op_sel_hi:[1,0]
	v_pk_mul_f32 v[164:165], v[164:165], 0.5 op_sel_hi:[1,0]
	v_pk_mul_f32 v[166:167], v[166:167], 0.5 op_sel_hi:[1,0]
	v_pk_mul_f32 v[168:169], v[168:169], 0.5 op_sel_hi:[1,0]
	v_pk_mul_f32 v[170:171], v[170:171], 0.5 op_sel_hi:[1,0]
	s_lshr_b32 s4, s54, 4
	s_add_u32 s4, s4, s53
	s_mov_b32 s5, 8
	s_cmp_eq_u32 s4, 1
	s_cbranch_scc1 .Lf9a_rg1
	s_cmp_eq_u32 s4, 2
	s_cbranch_scc1 .Lf9a_rg2
	s_cmp_eq_u32 s4, 3
	s_cbranch_scc1 .Lf9a_rg3
	s_cmp_eq_u32 s4, 4
	s_cbranch_scc1 .Lf9a_rg4
	s_cmp_eq_u32 s4, 5
	s_cbranch_scc1 .Lf9a_rg5
	s_cmp_eq_u32 s4, 6
	s_cbranch_scc1 .Lf9a_rg6
	s_cmp_eq_u32 s4, 7
	s_cbranch_scc1 .Lf9a_rg7

; __device__ __forceinline__ float rstd_from(const float* ssq, int row) {
;     const f32x4* p = (const f32x4*)(ssq + (size_t)row * 16);
;     const f32x4 s = (p[0] + p[1]) + (p[2] + p[3]);
;     return __builtin_amdgcn_rsqf(((s[0] + s[1]) + (s[2] + s[3])) * (1.0f / DM) + RMS_EPS);
; }
; __device__ __forceinline__ void p10_final(const Args& A, int lane, int wave, float* outp) {
;     const float* ssq = (const float*)(A.ws + WS_SSQF); const bf16_t* X3 = (const bf16_t*)(A.ws + WS_X3);
;     const int gw = blockIdx.x * 8 + wave, NGW = gridDim.x * 8;
;     for (int m = gw; m < M; m += NGW) { const float rs = pg8::rstd_from(ssq, m);
; #pragma unroll
;         for (int j = 0; j < 2; ++j) { const int c = 8 * lane + 512 * j; f32x4 a, b; pg8::unpack8(*(const u32x4*)(X3 + (size_t)m * DM + c), a, b);
;             *(f32x4*)(outp + (size_t)m * DM + c) = (a * rs) * *(const f32x4*)(A.g_final + c); *(f32x4*)(outp + (size_t)m * DM + c + 4) = (b * rs) * *(const f32x4*)(A.g_final + c + 4); } }
; }
.Lf9_sync_done:
	s_or_b64 exec, exec, s[30:31]
	s_barrier
	s_waitcnt lgkmcnt(0)
	s_lshl_b32 s4, s0, 2
	s_add_u32 s4, s100, s4
	s_addc_u32 s5, s101, 0
	global_load_dwordx4 v[168:171], v188, s[4:5] nt
	global_load_dwordx4 v[164:167], v188, s[4:5] offset:16 nt
	global_load_dwordx4 v[160:163], v188, s[4:5] offset:128 nt
	global_load_dwordx4 v[156:159], v188, s[4:5] offset:144 nt
	s_lshl_b32 s4, s1, 6
	s_add_u32 s38, s16, s4
	s_addc_u32 s39, s17, 0
	s_add_u32 s36, s38, 0x2000
	s_addc_u32 s37, s39, 0
	v_mov_b32_e32 v189, 0x358637bd
	v_lshl_add_u32 v228, v190, 10, v146
	global_load_dwordx4 v[196:199], v228, s[38:39] sc0 sc1
	global_load_dwordx4 v[200:203], v228, s[38:39] offset:16 sc0 sc1
	global_load_dwordx4 v[204:207], v228, s[38:39] offset:32 sc0 sc1
	global_load_dwordx4 v[208:211], v228, s[38:39] offset:48 sc0 sc1
	global_load_dwordx4 v[212:215], v228, s[36:37] sc0 sc1
	global_load_dwordx4 v[216:219], v228, s[36:37] offset:16 sc0 sc1
	global_load_dwordx4 v[240:243], v228, s[36:37] offset:32 sc0 sc1
	global_load_dwordx4 v[244:247], v228, s[36:37] offset:48 sc0 sc1
	v_lshlrev_b32_e32 v229, 2, v1
	v_add_u32_e32 v230, 0x40, v229
	v_add_u32_e32 v231, 0x80, v229
	v_add_u32_e32 v232, 0xc0, v229
	s_waitcnt vmcnt(4)
	v_pk_add_f32 v[198:199], v[198:199], v[202:203]
	v_pk_add_f32 v[196:197], v[196:197], v[200:201]
	v_pk_add_f32 v[200:201], v[206:207], v[210:211]
	v_pk_add_f32 v[202:203], v[204:205], v[208:209]
	v_pk_add_f32 v[198:199], v[198:199], v[200:201]
	v_pk_add_f32 v[196:197], v[196:197], v[202:203]
	v_add_f32_e32 v196, v196, v197
	v_add_f32_e32 v198, v198, v199
	v_add_f32_e32 v196, v196, v198
	v_fmamk_f32 v196, v196, 0x3a800000, v189
	v_rsq_f32_e32 v196, v196
	s_waitcnt vmcnt(0)
	v_pk_add_f32 v[214:215], v[214:215], v[218:219]
	v_pk_add_f32 v[212:213], v[212:213], v[216:217]
	v_pk_add_f32 v[216:217], v[242:243], v[246:247]
	v_pk_add_f32 v[218:219], v[240:241], v[244:245]
	v_pk_add_f32 v[214:215], v[214:215], v[216:217]
	v_pk_add_f32 v[212:213], v[212:213], v[218:219]
	v_add_f32_e32 v212, v212, v213
	v_add_f32_e32 v214, v214, v215
	v_add_f32_e32 v212, v212, v214
	v_fmamk_f32 v212, v212, 0x3a800000, v189
	v_rsq_f32_e32 v212, v212
	s_nop 0
	ds_bpermute_b32 v172, v229, v196
	ds_bpermute_b32 v173, v230, v196
	ds_bpermute_b32 v174, v231, v196
	ds_bpermute_b32 v175, v232, v196
	ds_bpermute_b32 v176, v229, v212
	ds_bpermute_b32 v177, v230, v212
	ds_bpermute_b32 v178, v231, v212
	ds_bpermute_b32 v179, v232, v212
	s_waitcnt lgkmcnt(0)
	s_lshl_b32 s4, s54, 7
	s_lshl_b32 s5, s53, 11
	s_add_i32 s4, s4, s5
	s_add_i32 s4, s4, 0x20000
	v_lshlrev_b32_e32 v228, 7, v1
	v_lshl_add_u32 v228, v190, 5, v228
	v_add_u32_e32 v228, s4, v228
	v_lshl_add_u32 v229, v195, 4, s4
	v_lshrrev_b32_e32 v230, 3, v195
	v_lshlrev_b32_e32 v230, 12, v230
	v_and_b32_e32 v231, 7, v195
	v_lshl_add_u32 v230, v231, 4, v230
	v_add_u32_e32 v231, 0x8000, v230
	s_lshl_b32 s4, s1, 12
	s_lshl_b32 s5, s0, 2
	s_add_u32 s4, s4, s5
	s_add_u32 s34, s76, s4
	s_addc_u32 s35, s77, 0
	s_lshr_b32 s4, s54, 4
	s_add_u32 s4, s4, s53
	s_mov_b32 s5, 8
	s_cmp_eq_u32 s4, 1
	s_cbranch_scc1 .Lf9d_rg1
	s_cmp_eq_u32 s4, 2
	s_cbranch_scc1 .Lf9d_rg2
	s_cmp_eq_u32 s4, 3
	s_cbranch_scc1 .Lf9d_rg3
	s_cmp_eq_u32 s4, 4
	s_cbranch_scc1 .Lf9d_rg4
	s_cmp_eq_u32 s4, 5
	s_cbranch_scc1 .Lf9d_rg5
	s_cmp_eq_u32 s4, 6
	s_cbranch_scc1 .Lf9d_rg6
	s_cmp_eq_u32 s4, 7
	s_cbranch_scc1 .Lf9d_rg7
